# Epi5 + Epi2 residual epilogues: preload ring for RMW loads (global saddr loads into free MFMA-fragment VGPRs), counted vmcnt
# baseline (speedup 1.0000x reference)
; __device__ __forceinline__ float sigmoid_f(float x) { return __builtin_amdgcn_rcpf(1.f + __builtin_amdgcn_exp2f(-1.4426950408889634f * x)); }
; __device__ __forceinline__ float bf_lo(unsigned u) { return __uint_as_float(u << 16); }
; __device__ __forceinline__ float bf_hi(unsigned u) { return __uint_as_float(u & 0xffff0000u); }
; __device__ __forceinline__ u32x4 pack8(const f32x4 v0, const f32x4 v1) { u32x4 w; w.x = cvt_pk_bf16(v0[0], v0[1]); w.y = cvt_pk_bf16(v0[2], v0[3]); w.z = cvt_pk_bf16(v1[0], v1[1]); w.w = cvt_pk_bf16(v1[2], v1[3]); return w; }
;     __device__ __forceinline__ void operator()(const f32x4 (&acc)[2][2][4][2], const Unit& u, int wr, int wc, int fr, int fq) const {
;     ...
; #pragma unroll
;             for (int ai = 0; ai < 2; ++ai)
; #pragma unroll
;                 for (int m = 0; m < 4; ++m) { const int r = row0 + ai * HALF + m * 16;
;                     float sc = 1.f; if (MODE == 0 || MODE == 4) sc = __builtin_amdgcn_rsqf(row_ssq(ssq, r) * inv_n + RMS_EPS);
; #pragma unroll
;                     for (int bj = 0; bj < 2; ++bj) { f32x4 v0 = acc[ai][bj][m][0], v1 = acc[ai][bj][m][1]; bf16_t* p = ob + (unsigned)(r * ld + col0 + bj * HALF);
;                         if constexpr (MODE == 0) { v0 = v0 * sc; v1 = v1 * sc; }
;                         if constexpr (MODE == 3) { v0 = (v0 + bv[bj][0]) * sv[bj][0]; v1 = (v1 + bv[bj][1]) * sv[bj][1]; }
;                         if constexpr (MODE == 4) {
; #pragma unroll
;                             for (int e = 0; e < 4; ++e) { v0[e] = sigmoid_f(v0[e] * sc); v1[e] = sigmoid_f(v1[e] * sc); } }
;                         if constexpr (MODE == 5) { const u32x4 g = *(const u32x4*)(G + (unsigned)(r * ld + col0 + bj * HALF));
;                             v0 = v0 * (f32x4){bf_lo(g.x), bf_hi(g.x), bf_lo(g.y), bf_hi(g.y)}; v1 = v1 * (f32x4){bf_lo(g.z), bf_hi(g.z), bf_lo(g.w), bf_hi(g.w)};
;                             if (!first) { const u32x4 q = *(const u32x4*)p; v0 = v0 + (f32x4){bf_lo(q.x), bf_hi(q.x), bf_lo(q.y), bf_hi(q.y)}; v1 = v1 + (f32x4){bf_lo(q.z), bf_hi(q.z), bf_lo(q.w), bf_hi(q.w)}; } }
;                         *(u32x4*)p = pack8(v0, v1); }
;                     if (MODE == 5 || MODE == 4) asm volatile("" ::: "memory"); }
.LBB0_108:
	s_mov_b64 s[46:47], s[54:55]
	s_mov_b64 s[28:29], 0
	s_mov_b64 s[42:43], 0
	s_mov_b64 s[50:51], 0
	s_mov_b64 s[74:75], 0
	s_mov_b64 s[80:81], 0
	s_mov_b64 s[50:51], s[36:37]
	s_mov_b32 s74, 0
	s_mov_b32 s75, 0
	s_mov_b64 s[28:29], 0
	s_mov_b64 s[42:43], 0
	v_mov_b32_e32 v2, v184
	s_lshl_b32 s25, s25, 8
	s_add_i32 s25, s25, s77
	v_and_or_b32 v142, v2, 15, s25
	s_lshl_b32 s25, s91, 8
	v_lshrrev_b32_e32 v2, 1, v2
	v_and_or_b32 v2, v2, 24, s25
	v_or_b32_e32 v148, s88, v2
	v_lshlrev_b32_e32 v149, 10, v142
	v_add_u32_e32 v2, v148, v149
	v_lshlrev_b32_e32 v2, 1, v2
	s_andn2_b64 s[42:43], exec, s[44:45]
	s_and_b64 vcc, exec, s[44:45]
	s_cbranch_vccz .Le5_first
	v_add_u32_e32 v226, 0x0, v2
	global_load_dwordx4 v[142:145], v226, s[50:51] offset:0
	global_load_dwordx4 v[148:151], v226, s[46:47] offset:0
	v_add_u32_e32 v226, 0x0, v2
	global_load_dwordx4 v[152:155], v226, s[50:51] offset:256
	global_load_dwordx4 v[156:159], v226, s[46:47] offset:256
	v_add_u32_e32 v226, 0x8000, v2
	global_load_dwordx4 v[160:163], v226, s[50:51] offset:0
	global_load_dwordx4 v[164:167], v226, s[46:47] offset:0
	v_add_u32_e32 v226, 0x8000, v2
	global_load_dwordx4 v[168:171], v226, s[50:51] offset:256
	global_load_dwordx4 v[172:175], v226, s[46:47] offset:256
	v_add_u32_e32 v226, 0x10000, v2
	global_load_dwordx4 v[176:179], v226, s[50:51] offset:0
	global_load_dwordx4 v[180:183], v226, s[46:47] offset:0
	v_add_u32_e32 v226, 0x10000, v2
	global_load_dwordx4 v[194:197], v226, s[50:51] offset:256
	global_load_dwordx4 v[198:201], v226, s[46:47] offset:256
	v_add_u32_e32 v226, 0x18000, v2
	global_load_dwordx4 v[202:205], v226, s[50:51] offset:0
	global_load_dwordx4 v[206:209], v226, s[46:47] offset:0
	s_waitcnt vmcnt(12)
	v_lshlrev_b32_e32 v220, 16, v142
	v_and_b32_e32 v221, 0xffff0000, v142
	v_pk_mul_f32 v[128:129], v[128:129], v[220:221]
	v_lshlrev_b32_e32 v222, 16, v143
	v_and_b32_e32 v223, 0xffff0000, v143
	v_pk_mul_f32 v[130:131], v[130:131], v[222:223]
	v_lshlrev_b32_e32 v224, 16, v144
	v_and_b32_e32 v225, 0xffff0000, v144
	v_pk_mul_f32 v[124:125], v[124:125], v[224:225]
	v_lshlrev_b32_e32 v220, 16, v145
	v_and_b32_e32 v221, 0xffff0000, v145
	v_pk_mul_f32 v[126:127], v[126:127], v[220:221]
	v_lshlrev_b32_e32 v220, 16, v148
	v_and_b32_e32 v221, 0xffff0000, v148
	v_pk_add_f32 v[128:129], v[128:129], v[220:221]
	v_lshlrev_b32_e32 v222, 16, v149
	v_and_b32_e32 v223, 0xffff0000, v149
	v_pk_add_f32 v[130:131], v[130:131], v[222:223]
	v_lshlrev_b32_e32 v224, 16, v150
	v_and_b32_e32 v225, 0xffff0000, v150
	v_pk_add_f32 v[124:125], v[124:125], v[224:225]
	v_lshlrev_b32_e32 v220, 16, v151
	v_and_b32_e32 v221, 0xffff0000, v151
	v_pk_add_f32 v[126:127], v[126:127], v[220:221]
	v_cvt_pk_bf16_f32 v128, v128, v129
	v_cvt_pk_bf16_f32 v129, v130, v131
	v_cvt_pk_bf16_f32 v130, v124, v125
	v_cvt_pk_bf16_f32 v131, v126, v127
	v_add_u32_e32 v226, 0x0, v2
	global_store_dwordx4 v226, v[128:131], s[46:47] offset:0
	v_add_u32_e32 v226, 0x18000, v2
	global_load_dwordx4 v[142:145], v226, s[50:51] offset:256
	global_load_dwordx4 v[148:151], v226, s[46:47] offset:256
	s_waitcnt vmcnt(13)
	v_lshlrev_b32_e32 v220, 16, v152
	v_and_b32_e32 v221, 0xffff0000, v152
	v_pk_mul_f32 v[120:121], v[120:121], v[220:221]
	v_lshlrev_b32_e32 v222, 16, v153
	v_and_b32_e32 v223, 0xffff0000, v153
	v_pk_mul_f32 v[122:123], v[122:123], v[222:223]
	v_lshlrev_b32_e32 v224, 16, v154
	v_and_b32_e32 v225, 0xffff0000, v154
	v_pk_mul_f32 v[116:117], v[116:117], v[224:225]
	v_lshlrev_b32_e32 v220, 16, v155
	v_and_b32_e32 v221, 0xffff0000, v155
	v_pk_mul_f32 v[118:119], v[118:119], v[220:221]
	v_lshlrev_b32_e32 v220, 16, v156
	v_and_b32_e32 v221, 0xffff0000, v156
	v_pk_add_f32 v[120:121], v[120:121], v[220:221]
	v_lshlrev_b32_e32 v222, 16, v157
	v_and_b32_e32 v223, 0xffff0000, v157
	v_pk_add_f32 v[122:123], v[122:123], v[222:223]
	v_lshlrev_b32_e32 v224, 16, v158
	v_and_b32_e32 v225, 0xffff0000, v158
	v_pk_add_f32 v[116:117], v[116:117], v[224:225]
	v_lshlrev_b32_e32 v220, 16, v159
	v_and_b32_e32 v221, 0xffff0000, v159
	v_pk_add_f32 v[118:119], v[118:119], v[220:221]
	v_cvt_pk_bf16_f32 v120, v120, v121
	v_cvt_pk_bf16_f32 v121, v122, v123
	v_cvt_pk_bf16_f32 v122, v116, v117
	v_cvt_pk_bf16_f32 v123, v118, v119
	v_add_u32_e32 v226, 0x0, v2
	global_store_dwordx4 v226, v[120:123], s[46:47] offset:256
	v_add_u32_e32 v226, 0x40000, v2
	global_load_dwordx4 v[152:155], v226, s[50:51] offset:0
	global_load_dwordx4 v[156:159], v226, s[46:47] offset:0
	s_waitcnt vmcnt(14)
	v_lshlrev_b32_e32 v220, 16, v160
	v_and_b32_e32 v221, 0xffff0000, v160
	v_pk_mul_f32 v[112:113], v[112:113], v[220:221]
	v_lshlrev_b32_e32 v222, 16, v161
	v_and_b32_e32 v223, 0xffff0000, v161
	v_pk_mul_f32 v[114:115], v[114:115], v[222:223]
	v_lshlrev_b32_e32 v224, 16, v162
	v_and_b32_e32 v225, 0xffff0000, v162
	v_pk_mul_f32 v[108:109], v[108:109], v[224:225]
	v_lshlrev_b32_e32 v220, 16, v163
	v_and_b32_e32 v221, 0xffff0000, v163
	v_pk_mul_f32 v[110:111], v[110:111], v[220:221]
	v_lshlrev_b32_e32 v220, 16, v164
	v_and_b32_e32 v221, 0xffff0000, v164
	v_pk_add_f32 v[112:113], v[112:113], v[220:221]
	v_lshlrev_b32_e32 v222, 16, v165
	v_and_b32_e32 v223, 0xffff0000, v165
	v_pk_add_f32 v[114:115], v[114:115], v[222:223]
	v_lshlrev_b32_e32 v224, 16, v166
	v_and_b32_e32 v225, 0xffff0000, v166
	v_pk_add_f32 v[108:109], v[108:109], v[224:225]
	v_lshlrev_b32_e32 v220, 16, v167
	v_and_b32_e32 v221, 0xffff0000, v167
	v_pk_add_f32 v[110:111], v[110:111], v[220:221]
	v_cvt_pk_bf16_f32 v112, v112, v113
	v_cvt_pk_bf16_f32 v113, v114, v115
	v_cvt_pk_bf16_f32 v114, v108, v109
	v_cvt_pk_bf16_f32 v115, v110, v111
	v_add_u32_e32 v226, 0x8000, v2
	global_store_dwordx4 v226, v[112:115], s[46:47] offset:0
	v_add_u32_e32 v226, 0x40000, v2
	global_load_dwordx4 v[160:163], v226, s[50:51] offset:256
	global_load_dwordx4 v[164:167], v226, s[46:47] offset:256
	s_waitcnt vmcnt(15)
; __device__ __forceinline__ float sigmoid_f(float x) { return __builtin_amdgcn_rcpf(1.f + __builtin_amdgcn_exp2f(-1.4426950408889634f * x)); }
; __device__ __forceinline__ float bf_lo(unsigned u) { return __uint_as_float(u << 16); }
; __device__ __forceinline__ float bf_hi(unsigned u) { return __uint_as_float(u & 0xffff0000u); }
; __device__ __forceinline__ u32x4 pack8(const f32x4 v0, const f32x4 v1) { u32x4 w; w.x = cvt_pk_bf16(v0[0], v0[1]); w.y = cvt_pk_bf16(v0[2], v0[3]); w.z = cvt_pk_bf16(v1[0], v1[1]); w.w = cvt_pk_bf16(v1[2], v1[3]); return w; }
;     __device__ __forceinline__ void operator()(const f32x4 (&acc)[2][2][4][2], const Unit& u, int wr, int wc, int fr, int fq) const {
;     ...
;                     for (int bj = 0; bj < 2; ++bj) { f32x4 v0 = acc[ai][bj][m][0], v1 = acc[ai][bj][m][1]; bf16_t* p = ob + (unsigned)(r * ld + col0 + bj * HALF);
;                         if constexpr (MODE == 0) { v0 = v0 * sc; v1 = v1 * sc; }
;                         if constexpr (MODE == 3) { v0 = (v0 + bv[bj][0]) * sv[bj][0]; v1 = (v1 + bv[bj][1]) * sv[bj][1]; }
;                         if constexpr (MODE == 4) {
; #pragma unroll
;                             for (int e = 0; e < 4; ++e) { v0[e] = sigmoid_f(v0[e] * sc); v1[e] = sigmoid_f(v1[e] * sc); } }
;                         if constexpr (MODE == 5) { const u32x4 g = *(const u32x4*)(G + (unsigned)(r * ld + col0 + bj * HALF));
;                             v0 = v0 * (f32x4){bf_lo(g.x), bf_hi(g.x), bf_lo(g.y), bf_hi(g.y)}; v1 = v1 * (f32x4){bf_lo(g.z), bf_hi(g.z), bf_lo(g.w), bf_hi(g.w)};
;                             if (!first) { const u32x4 q = *(const u32x4*)p; v0 = v0 + (f32x4){bf_lo(q.x), bf_hi(q.x), bf_lo(q.y), bf_hi(q.y)}; v1 = v1 + (f32x4){bf_lo(q.z), bf_hi(q.z), bf_lo(q.w), bf_hi(q.w)}; } }
;                         *(u32x4*)p = pack8(v0, v1); }
	v_lshlrev_b32_e32 v220, 16, v168
	v_and_b32_e32 v221, 0xffff0000, v168
	v_pk_mul_f32 v[104:105], v[104:105], v[220:221]
	v_lshlrev_b32_e32 v222, 16, v169
	v_and_b32_e32 v223, 0xffff0000, v169
	v_pk_mul_f32 v[106:107], v[106:107], v[222:223]
	v_lshlrev_b32_e32 v224, 16, v170
	v_and_b32_e32 v225, 0xffff0000, v170
	v_pk_mul_f32 v[100:101], v[100:101], v[224:225]
	v_lshlrev_b32_e32 v220, 16, v171
	v_and_b32_e32 v221, 0xffff0000, v171
	v_pk_mul_f32 v[102:103], v[102:103], v[220:221]
	v_lshlrev_b32_e32 v220, 16, v172
	v_and_b32_e32 v221, 0xffff0000, v172
	v_pk_add_f32 v[104:105], v[104:105], v[220:221]
	v_lshlrev_b32_e32 v222, 16, v173
	v_and_b32_e32 v223, 0xffff0000, v173
	v_pk_add_f32 v[106:107], v[106:107], v[222:223]
	v_lshlrev_b32_e32 v224, 16, v174
	v_and_b32_e32 v225, 0xffff0000, v174
	v_pk_add_f32 v[100:101], v[100:101], v[224:225]
	v_lshlrev_b32_e32 v220, 16, v175
	v_and_b32_e32 v221, 0xffff0000, v175
	v_pk_add_f32 v[102:103], v[102:103], v[220:221]
	v_cvt_pk_bf16_f32 v104, v104, v105
	v_cvt_pk_bf16_f32 v105, v106, v107
	v_cvt_pk_bf16_f32 v106, v100, v101
	v_cvt_pk_bf16_f32 v107, v102, v103
	v_add_u32_e32 v226, 0x8000, v2
	global_store_dwordx4 v226, v[104:107], s[46:47] offset:256
	v_add_u32_e32 v226, 0x48000, v2
	global_load_dwordx4 v[168:171], v226, s[50:51] offset:0
	global_load_dwordx4 v[172:175], v226, s[46:47] offset:0
	s_waitcnt vmcnt(16)
	v_lshlrev_b32_e32 v220, 16, v176
	v_and_b32_e32 v221, 0xffff0000, v176
	v_pk_mul_f32 v[96:97], v[96:97], v[220:221]
	v_lshlrev_b32_e32 v222, 16, v177
	v_and_b32_e32 v223, 0xffff0000, v177
	v_pk_mul_f32 v[98:99], v[98:99], v[222:223]
	v_lshlrev_b32_e32 v224, 16, v178
	v_and_b32_e32 v225, 0xffff0000, v178
	v_pk_mul_f32 v[92:93], v[92:93], v[224:225]
	v_lshlrev_b32_e32 v220, 16, v179
	v_and_b32_e32 v221, 0xffff0000, v179
	v_pk_mul_f32 v[94:95], v[94:95], v[220:221]
	v_lshlrev_b32_e32 v220, 16, v180
	v_and_b32_e32 v221, 0xffff0000, v180
	v_pk_add_f32 v[96:97], v[96:97], v[220:221]
	v_lshlrev_b32_e32 v222, 16, v181
	v_and_b32_e32 v223, 0xffff0000, v181
	v_pk_add_f32 v[98:99], v[98:99], v[222:223]
	v_lshlrev_b32_e32 v224, 16, v182
	v_and_b32_e32 v225, 0xffff0000, v182
	v_pk_add_f32 v[92:93], v[92:93], v[224:225]
	v_lshlrev_b32_e32 v220, 16, v183
	v_and_b32_e32 v221, 0xffff0000, v183
	v_pk_add_f32 v[94:95], v[94:95], v[220:221]
	v_cvt_pk_bf16_f32 v96, v96, v97
	v_cvt_pk_bf16_f32 v97, v98, v99
	v_cvt_pk_bf16_f32 v98, v92, v93
	v_cvt_pk_bf16_f32 v99, v94, v95
	v_add_u32_e32 v226, 0x10000, v2
	global_store_dwordx4 v226, v[96:99], s[46:47] offset:0
	v_add_u32_e32 v226, 0x48000, v2
	global_load_dwordx4 v[176:179], v226, s[50:51] offset:256
	global_load_dwordx4 v[180:183], v226, s[46:47] offset:256
	s_waitcnt vmcnt(17)
	v_lshlrev_b32_e32 v220, 16, v194
	v_and_b32_e32 v221, 0xffff0000, v194
	v_pk_mul_f32 v[88:89], v[88:89], v[220:221]
	v_lshlrev_b32_e32 v222, 16, v195
	v_and_b32_e32 v223, 0xffff0000, v195
	v_pk_mul_f32 v[90:91], v[90:91], v[222:223]
	v_lshlrev_b32_e32 v224, 16, v196
	v_and_b32_e32 v225, 0xffff0000, v196
	v_pk_mul_f32 v[84:85], v[84:85], v[224:225]
	v_lshlrev_b32_e32 v220, 16, v197
	v_and_b32_e32 v221, 0xffff0000, v197
	v_pk_mul_f32 v[86:87], v[86:87], v[220:221]
	v_lshlrev_b32_e32 v220, 16, v198
	v_and_b32_e32 v221, 0xffff0000, v198
	v_pk_add_f32 v[88:89], v[88:89], v[220:221]
	v_lshlrev_b32_e32 v222, 16, v199
	v_and_b32_e32 v223, 0xffff0000, v199
	v_pk_add_f32 v[90:91], v[90:91], v[222:223]
	v_lshlrev_b32_e32 v224, 16, v200
	v_and_b32_e32 v225, 0xffff0000, v200
	v_pk_add_f32 v[84:85], v[84:85], v[224:225]
	v_lshlrev_b32_e32 v220, 16, v201
	v_and_b32_e32 v221, 0xffff0000, v201
	v_pk_add_f32 v[86:87], v[86:87], v[220:221]
	v_cvt_pk_bf16_f32 v88, v88, v89
	v_cvt_pk_bf16_f32 v89, v90, v91
	v_cvt_pk_bf16_f32 v90, v84, v85
	v_cvt_pk_bf16_f32 v91, v86, v87
	v_add_u32_e32 v226, 0x10000, v2
	global_store_dwordx4 v226, v[88:91], s[46:47] offset:256
	v_add_u32_e32 v226, 0x50000, v2
	global_load_dwordx4 v[194:197], v226, s[50:51] offset:0
	global_load_dwordx4 v[198:201], v226, s[46:47] offset:0
	s_waitcnt vmcnt(18)
	v_lshlrev_b32_e32 v220, 16, v202
	v_and_b32_e32 v221, 0xffff0000, v202
	v_pk_mul_f32 v[80:81], v[80:81], v[220:221]
	v_lshlrev_b32_e32 v222, 16, v203
	v_and_b32_e32 v223, 0xffff0000, v203
	v_pk_mul_f32 v[82:83], v[82:83], v[222:223]
	v_lshlrev_b32_e32 v224, 16, v204
	v_and_b32_e32 v225, 0xffff0000, v204
	v_pk_mul_f32 v[76:77], v[76:77], v[224:225]
	v_lshlrev_b32_e32 v220, 16, v205
	v_and_b32_e32 v221, 0xffff0000, v205
	v_pk_mul_f32 v[78:79], v[78:79], v[220:221]
	v_lshlrev_b32_e32 v220, 16, v206
	v_and_b32_e32 v221, 0xffff0000, v206
	v_pk_add_f32 v[80:81], v[80:81], v[220:221]
	v_lshlrev_b32_e32 v222, 16, v207
	v_and_b32_e32 v223, 0xffff0000, v207
	v_pk_add_f32 v[82:83], v[82:83], v[222:223]
	v_lshlrev_b32_e32 v224, 16, v208
	v_and_b32_e32 v225, 0xffff0000, v208
	v_pk_add_f32 v[76:77], v[76:77], v[224:225]
	v_lshlrev_b32_e32 v220, 16, v209
	v_and_b32_e32 v221, 0xffff0000, v209
	v_pk_add_f32 v[78:79], v[78:79], v[220:221]
	v_cvt_pk_bf16_f32 v80, v80, v81
	v_cvt_pk_bf16_f32 v81, v82, v83
	v_cvt_pk_bf16_f32 v82, v76, v77
	v_cvt_pk_bf16_f32 v83, v78, v79
	v_add_u32_e32 v226, 0x18000, v2
	global_store_dwordx4 v226, v[80:83], s[46:47] offset:0
	v_add_u32_e32 v226, 0x50000, v2
	global_load_dwordx4 v[202:205], v226, s[50:51] offset:256
	global_load_dwordx4 v[206:209], v226, s[46:47] offset:256
	s_waitcnt vmcnt(18)
; __device__ __forceinline__ float sigmoid_f(float x) { return __builtin_amdgcn_rcpf(1.f + __builtin_amdgcn_exp2f(-1.4426950408889634f * x)); }
; __device__ __forceinline__ float bf_lo(unsigned u) { return __uint_as_float(u << 16); }
; __device__ __forceinline__ float bf_hi(unsigned u) { return __uint_as_float(u & 0xffff0000u); }
; __device__ __forceinline__ u32x4 pack8(const f32x4 v0, const f32x4 v1) { u32x4 w; w.x = cvt_pk_bf16(v0[0], v0[1]); w.y = cvt_pk_bf16(v0[2], v0[3]); w.z = cvt_pk_bf16(v1[0], v1[1]); w.w = cvt_pk_bf16(v1[2], v1[3]); return w; }
;     __device__ __forceinline__ void operator()(const f32x4 (&acc)[2][2][4][2], const Unit& u, int wr, int wc, int fr, int fq) const {
;     ...
;                     for (int bj = 0; bj < 2; ++bj) { f32x4 v0 = acc[ai][bj][m][0], v1 = acc[ai][bj][m][1]; bf16_t* p = ob + (unsigned)(r * ld + col0 + bj * HALF);
;                         if constexpr (MODE == 0) { v0 = v0 * sc; v1 = v1 * sc; }
;                         if constexpr (MODE == 3) { v0 = (v0 + bv[bj][0]) * sv[bj][0]; v1 = (v1 + bv[bj][1]) * sv[bj][1]; }
;                         if constexpr (MODE == 4) {
; #pragma unroll
;                             for (int e = 0; e < 4; ++e) { v0[e] = sigmoid_f(v0[e] * sc); v1[e] = sigmoid_f(v1[e] * sc); } }
;                         if constexpr (MODE == 5) { const u32x4 g = *(const u32x4*)(G + (unsigned)(r * ld + col0 + bj * HALF));
;                             v0 = v0 * (f32x4){bf_lo(g.x), bf_hi(g.x), bf_lo(g.y), bf_hi(g.y)}; v1 = v1 * (f32x4){bf_lo(g.z), bf_hi(g.z), bf_lo(g.w), bf_hi(g.w)};
;                             if (!first) { const u32x4 q = *(const u32x4*)p; v0 = v0 + (f32x4){bf_lo(q.x), bf_hi(q.x), bf_lo(q.y), bf_hi(q.y)}; v1 = v1 + (f32x4){bf_lo(q.z), bf_hi(q.z), bf_lo(q.w), bf_hi(q.w)}; } }
;                         *(u32x4*)p = pack8(v0, v1); }
	v_lshlrev_b32_e32 v220, 16, v142
	v_and_b32_e32 v221, 0xffff0000, v142
	v_pk_mul_f32 v[72:73], v[72:73], v[220:221]
	v_lshlrev_b32_e32 v222, 16, v143
	v_and_b32_e32 v223, 0xffff0000, v143
	v_pk_mul_f32 v[74:75], v[74:75], v[222:223]
	v_lshlrev_b32_e32 v224, 16, v144
	v_and_b32_e32 v225, 0xffff0000, v144
	v_pk_mul_f32 v[68:69], v[68:69], v[224:225]
	v_lshlrev_b32_e32 v220, 16, v145
	v_and_b32_e32 v221, 0xffff0000, v145
	v_pk_mul_f32 v[70:71], v[70:71], v[220:221]
	v_lshlrev_b32_e32 v220, 16, v148
	v_and_b32_e32 v221, 0xffff0000, v148
	v_pk_add_f32 v[72:73], v[72:73], v[220:221]
	v_lshlrev_b32_e32 v222, 16, v149
	v_and_b32_e32 v223, 0xffff0000, v149
	v_pk_add_f32 v[74:75], v[74:75], v[222:223]
	v_lshlrev_b32_e32 v224, 16, v150
	v_and_b32_e32 v225, 0xffff0000, v150
	v_pk_add_f32 v[68:69], v[68:69], v[224:225]
	v_lshlrev_b32_e32 v220, 16, v151
	v_and_b32_e32 v221, 0xffff0000, v151
	v_pk_add_f32 v[70:71], v[70:71], v[220:221]
	v_cvt_pk_bf16_f32 v72, v72, v73
	v_cvt_pk_bf16_f32 v73, v74, v75
	v_cvt_pk_bf16_f32 v74, v68, v69
	v_cvt_pk_bf16_f32 v75, v70, v71
	v_add_u32_e32 v226, 0x18000, v2
	global_store_dwordx4 v226, v[72:75], s[46:47] offset:256
	v_add_u32_e32 v226, 0x58000, v2
	global_load_dwordx4 v[142:145], v226, s[50:51] offset:0
	global_load_dwordx4 v[148:151], v226, s[46:47] offset:0
	s_waitcnt vmcnt(18)
	v_lshlrev_b32_e32 v220, 16, v152
	v_and_b32_e32 v221, 0xffff0000, v152
	v_pk_mul_f32 v[64:65], v[64:65], v[220:221]
	v_lshlrev_b32_e32 v222, 16, v153
	v_and_b32_e32 v223, 0xffff0000, v153
	v_pk_mul_f32 v[66:67], v[66:67], v[222:223]
	v_lshlrev_b32_e32 v224, 16, v154
	v_and_b32_e32 v225, 0xffff0000, v154
	v_pk_mul_f32 v[60:61], v[60:61], v[224:225]
	v_lshlrev_b32_e32 v220, 16, v155
	v_and_b32_e32 v221, 0xffff0000, v155
	v_pk_mul_f32 v[62:63], v[62:63], v[220:221]
	v_lshlrev_b32_e32 v220, 16, v156
	v_and_b32_e32 v221, 0xffff0000, v156
	v_pk_add_f32 v[64:65], v[64:65], v[220:221]
	v_lshlrev_b32_e32 v222, 16, v157
	v_and_b32_e32 v223, 0xffff0000, v157
	v_pk_add_f32 v[66:67], v[66:67], v[222:223]
	v_lshlrev_b32_e32 v224, 16, v158
	v_and_b32_e32 v225, 0xffff0000, v158
	v_pk_add_f32 v[60:61], v[60:61], v[224:225]
	v_lshlrev_b32_e32 v220, 16, v159
	v_and_b32_e32 v221, 0xffff0000, v159
	v_pk_add_f32 v[62:63], v[62:63], v[220:221]
	v_cvt_pk_bf16_f32 v64, v64, v65
	v_cvt_pk_bf16_f32 v65, v66, v67
	v_cvt_pk_bf16_f32 v66, v60, v61
	v_cvt_pk_bf16_f32 v67, v62, v63
	v_add_u32_e32 v226, 0x40000, v2
	global_store_dwordx4 v226, v[64:67], s[46:47] offset:0
	v_add_u32_e32 v226, 0x58000, v2
	global_load_dwordx4 v[152:155], v226, s[50:51] offset:256
	global_load_dwordx4 v[156:159], v226, s[46:47] offset:256
	s_waitcnt vmcnt(18)
	v_lshlrev_b32_e32 v220, 16, v160
	v_and_b32_e32 v221, 0xffff0000, v160
	v_pk_mul_f32 v[56:57], v[56:57], v[220:221]
	v_lshlrev_b32_e32 v222, 16, v161
	v_and_b32_e32 v223, 0xffff0000, v161
	v_pk_mul_f32 v[58:59], v[58:59], v[222:223]
	v_lshlrev_b32_e32 v224, 16, v162
	v_and_b32_e32 v225, 0xffff0000, v162
	v_pk_mul_f32 v[52:53], v[52:53], v[224:225]
	v_lshlrev_b32_e32 v220, 16, v163
	v_and_b32_e32 v221, 0xffff0000, v163
	v_pk_mul_f32 v[54:55], v[54:55], v[220:221]
	v_lshlrev_b32_e32 v220, 16, v164
	v_and_b32_e32 v221, 0xffff0000, v164
	v_pk_add_f32 v[56:57], v[56:57], v[220:221]
	v_lshlrev_b32_e32 v222, 16, v165
	v_and_b32_e32 v223, 0xffff0000, v165
	v_pk_add_f32 v[58:59], v[58:59], v[222:223]
	v_lshlrev_b32_e32 v224, 16, v166
	v_and_b32_e32 v225, 0xffff0000, v166
	v_pk_add_f32 v[52:53], v[52:53], v[224:225]
	v_lshlrev_b32_e32 v220, 16, v167
	v_and_b32_e32 v221, 0xffff0000, v167
	v_pk_add_f32 v[54:55], v[54:55], v[220:221]
	v_cvt_pk_bf16_f32 v56, v56, v57
	v_cvt_pk_bf16_f32 v57, v58, v59
	v_cvt_pk_bf16_f32 v58, v52, v53
	v_cvt_pk_bf16_f32 v59, v54, v55
	v_add_u32_e32 v226, 0x40000, v2
	global_store_dwordx4 v226, v[56:59], s[46:47] offset:256
	s_waitcnt vmcnt(16)
	v_lshlrev_b32_e32 v220, 16, v168
	v_and_b32_e32 v221, 0xffff0000, v168
	v_pk_mul_f32 v[48:49], v[48:49], v[220:221]
	v_lshlrev_b32_e32 v222, 16, v169
	v_and_b32_e32 v223, 0xffff0000, v169
	v_pk_mul_f32 v[50:51], v[50:51], v[222:223]
	v_lshlrev_b32_e32 v224, 16, v170
	v_and_b32_e32 v225, 0xffff0000, v170
	v_pk_mul_f32 v[44:45], v[44:45], v[224:225]
	v_lshlrev_b32_e32 v220, 16, v171
	v_and_b32_e32 v221, 0xffff0000, v171
	v_pk_mul_f32 v[46:47], v[46:47], v[220:221]
	v_lshlrev_b32_e32 v220, 16, v172
	v_and_b32_e32 v221, 0xffff0000, v172
	v_pk_add_f32 v[48:49], v[48:49], v[220:221]
	v_lshlrev_b32_e32 v222, 16, v173
	v_and_b32_e32 v223, 0xffff0000, v173
	v_pk_add_f32 v[50:51], v[50:51], v[222:223]
	v_lshlrev_b32_e32 v224, 16, v174
	v_and_b32_e32 v225, 0xffff0000, v174
	v_pk_add_f32 v[44:45], v[44:45], v[224:225]
	v_lshlrev_b32_e32 v220, 16, v175
	v_and_b32_e32 v221, 0xffff0000, v175
	v_pk_add_f32 v[46:47], v[46:47], v[220:221]
	v_cvt_pk_bf16_f32 v48, v48, v49
	v_cvt_pk_bf16_f32 v49, v50, v51
	v_cvt_pk_bf16_f32 v50, v44, v45
	v_cvt_pk_bf16_f32 v51, v46, v47
	v_add_u32_e32 v226, 0x48000, v2
	global_store_dwordx4 v226, v[48:51], s[46:47] offset:0
	s_waitcnt vmcnt(14)
	v_lshlrev_b32_e32 v220, 16, v176
	v_and_b32_e32 v221, 0xffff0000, v176
	v_pk_mul_f32 v[40:41], v[40:41], v[220:221]
	v_lshlrev_b32_e32 v222, 16, v177
	v_and_b32_e32 v223, 0xffff0000, v177
	v_pk_mul_f32 v[42:43], v[42:43], v[222:223]
	v_lshlrev_b32_e32 v224, 16, v178
	v_and_b32_e32 v225, 0xffff0000, v178
	v_pk_mul_f32 v[36:37], v[36:37], v[224:225]
	v_lshlrev_b32_e32 v220, 16, v179
	v_and_b32_e32 v221, 0xffff0000, v179
	v_pk_mul_f32 v[38:39], v[38:39], v[220:221]
	v_lshlrev_b32_e32 v220, 16, v180
	v_and_b32_e32 v221, 0xffff0000, v180
	v_pk_add_f32 v[40:41], v[40:41], v[220:221]
	v_lshlrev_b32_e32 v222, 16, v181
	v_and_b32_e32 v223, 0xffff0000, v181
	v_pk_add_f32 v[42:43], v[42:43], v[222:223]
	v_lshlrev_b32_e32 v224, 16, v182
	v_and_b32_e32 v225, 0xffff0000, v182
	v_pk_add_f32 v[36:37], v[36:37], v[224:225]
	v_lshlrev_b32_e32 v220, 16, v183
	v_and_b32_e32 v221, 0xffff0000, v183
	v_pk_add_f32 v[38:39], v[38:39], v[220:221]
	v_cvt_pk_bf16_f32 v40, v40, v41
	v_cvt_pk_bf16_f32 v41, v42, v43
	v_cvt_pk_bf16_f32 v42, v36, v37
	v_cvt_pk_bf16_f32 v43, v38, v39
	v_add_u32_e32 v226, 0x48000, v2
	global_store_dwordx4 v226, v[40:43], s[46:47] offset:256
	s_waitcnt vmcnt(12)
; __device__ __forceinline__ float sigmoid_f(float x) { return __builtin_amdgcn_rcpf(1.f + __builtin_amdgcn_exp2f(-1.4426950408889634f * x)); }
; __device__ __forceinline__ float bf_lo(unsigned u) { return __uint_as_float(u << 16); }
; __device__ __forceinline__ float bf_hi(unsigned u) { return __uint_as_float(u & 0xffff0000u); }
; __device__ __forceinline__ u32x4 pack8(const f32x4 v0, const f32x4 v1) { u32x4 w; w.x = cvt_pk_bf16(v0[0], v0[1]); w.y = cvt_pk_bf16(v0[2], v0[3]); w.z = cvt_pk_bf16(v1[0], v1[1]); w.w = cvt_pk_bf16(v1[2], v1[3]); return w; }
;     __device__ __forceinline__ void operator()(const f32x4 (&acc)[2][2][4][2], const Unit& u, int wr, int wc, int fr, int fq) const {
;     ...
;                     for (int bj = 0; bj < 2; ++bj) { f32x4 v0 = acc[ai][bj][m][0], v1 = acc[ai][bj][m][1]; bf16_t* p = ob + (unsigned)(r * ld + col0 + bj * HALF);
;                         if constexpr (MODE == 0) { v0 = v0 * sc; v1 = v1 * sc; }
;                         if constexpr (MODE == 3) { v0 = (v0 + bv[bj][0]) * sv[bj][0]; v1 = (v1 + bv[bj][1]) * sv[bj][1]; }
;                         if constexpr (MODE == 4) {
; #pragma unroll
;                             for (int e = 0; e < 4; ++e) { v0[e] = sigmoid_f(v0[e] * sc); v1[e] = sigmoid_f(v1[e] * sc); } }
;                         if constexpr (MODE == 5) { const u32x4 g = *(const u32x4*)(G + (unsigned)(r * ld + col0 + bj * HALF));
;                             v0 = v0 * (f32x4){bf_lo(g.x), bf_hi(g.x), bf_lo(g.y), bf_hi(g.y)}; v1 = v1 * (f32x4){bf_lo(g.z), bf_hi(g.z), bf_lo(g.w), bf_hi(g.w)};
;                             if (!first) { const u32x4 q = *(const u32x4*)p; v0 = v0 + (f32x4){bf_lo(q.x), bf_hi(q.x), bf_lo(q.y), bf_hi(q.y)}; v1 = v1 + (f32x4){bf_lo(q.z), bf_hi(q.z), bf_lo(q.w), bf_hi(q.w)}; } }
;                         *(u32x4*)p = pack8(v0, v1); }
	v_lshlrev_b32_e32 v220, 16, v194
	v_and_b32_e32 v221, 0xffff0000, v194
	v_pk_mul_f32 v[32:33], v[32:33], v[220:221]
	v_lshlrev_b32_e32 v222, 16, v195
	v_and_b32_e32 v223, 0xffff0000, v195
	v_pk_mul_f32 v[34:35], v[34:35], v[222:223]
	v_lshlrev_b32_e32 v224, 16, v196
	v_and_b32_e32 v225, 0xffff0000, v196
	v_pk_mul_f32 v[28:29], v[28:29], v[224:225]
	v_lshlrev_b32_e32 v220, 16, v197
	v_and_b32_e32 v221, 0xffff0000, v197
	v_pk_mul_f32 v[30:31], v[30:31], v[220:221]
	v_lshlrev_b32_e32 v220, 16, v198
	v_and_b32_e32 v221, 0xffff0000, v198
	v_pk_add_f32 v[32:33], v[32:33], v[220:221]
	v_lshlrev_b32_e32 v222, 16, v199
	v_and_b32_e32 v223, 0xffff0000, v199
	v_pk_add_f32 v[34:35], v[34:35], v[222:223]
	v_lshlrev_b32_e32 v224, 16, v200
	v_and_b32_e32 v225, 0xffff0000, v200
	v_pk_add_f32 v[28:29], v[28:29], v[224:225]
	v_lshlrev_b32_e32 v220, 16, v201
	v_and_b32_e32 v221, 0xffff0000, v201
	v_pk_add_f32 v[30:31], v[30:31], v[220:221]
	v_cvt_pk_bf16_f32 v32, v32, v33
	v_cvt_pk_bf16_f32 v33, v34, v35
	v_cvt_pk_bf16_f32 v34, v28, v29
	v_cvt_pk_bf16_f32 v35, v30, v31
	v_add_u32_e32 v226, 0x50000, v2
	global_store_dwordx4 v226, v[32:35], s[46:47] offset:0
	s_waitcnt vmcnt(10)
	v_lshlrev_b32_e32 v220, 16, v202
	v_and_b32_e32 v221, 0xffff0000, v202
	v_pk_mul_f32 v[24:25], v[24:25], v[220:221]
	v_lshlrev_b32_e32 v222, 16, v203
	v_and_b32_e32 v223, 0xffff0000, v203
	v_pk_mul_f32 v[26:27], v[26:27], v[222:223]
	v_lshlrev_b32_e32 v224, 16, v204
	v_and_b32_e32 v225, 0xffff0000, v204
	v_pk_mul_f32 v[20:21], v[20:21], v[224:225]
	v_lshlrev_b32_e32 v220, 16, v205
	v_and_b32_e32 v221, 0xffff0000, v205
	v_pk_mul_f32 v[22:23], v[22:23], v[220:221]
	v_lshlrev_b32_e32 v220, 16, v206
	v_and_b32_e32 v221, 0xffff0000, v206
	v_pk_add_f32 v[24:25], v[24:25], v[220:221]
	v_lshlrev_b32_e32 v222, 16, v207
	v_and_b32_e32 v223, 0xffff0000, v207
	v_pk_add_f32 v[26:27], v[26:27], v[222:223]
	v_lshlrev_b32_e32 v224, 16, v208
	v_and_b32_e32 v225, 0xffff0000, v208
	v_pk_add_f32 v[20:21], v[20:21], v[224:225]
	v_lshlrev_b32_e32 v220, 16, v209
	v_and_b32_e32 v221, 0xffff0000, v209
	v_pk_add_f32 v[22:23], v[22:23], v[220:221]
	v_cvt_pk_bf16_f32 v24, v24, v25
	v_cvt_pk_bf16_f32 v25, v26, v27
	v_cvt_pk_bf16_f32 v26, v20, v21
	v_cvt_pk_bf16_f32 v27, v22, v23
	v_add_u32_e32 v226, 0x50000, v2
	global_store_dwordx4 v226, v[24:27], s[46:47] offset:256
	s_waitcnt vmcnt(8)
	v_lshlrev_b32_e32 v220, 16, v142
	v_and_b32_e32 v221, 0xffff0000, v142
	v_pk_mul_f32 v[16:17], v[16:17], v[220:221]
	v_lshlrev_b32_e32 v222, 16, v143
	v_and_b32_e32 v223, 0xffff0000, v143
	v_pk_mul_f32 v[18:19], v[18:19], v[222:223]
	v_lshlrev_b32_e32 v224, 16, v144
	v_and_b32_e32 v225, 0xffff0000, v144
	v_pk_mul_f32 v[12:13], v[12:13], v[224:225]
	v_lshlrev_b32_e32 v220, 16, v145
	v_and_b32_e32 v221, 0xffff0000, v145
	v_pk_mul_f32 v[14:15], v[14:15], v[220:221]
	v_lshlrev_b32_e32 v220, 16, v148
	v_and_b32_e32 v221, 0xffff0000, v148
	v_pk_add_f32 v[16:17], v[16:17], v[220:221]
	v_lshlrev_b32_e32 v222, 16, v149
	v_and_b32_e32 v223, 0xffff0000, v149
	v_pk_add_f32 v[18:19], v[18:19], v[222:223]
	v_lshlrev_b32_e32 v224, 16, v150
	v_and_b32_e32 v225, 0xffff0000, v150
	v_pk_add_f32 v[12:13], v[12:13], v[224:225]
	v_lshlrev_b32_e32 v220, 16, v151
	v_and_b32_e32 v221, 0xffff0000, v151
	v_pk_add_f32 v[14:15], v[14:15], v[220:221]
	v_cvt_pk_bf16_f32 v16, v16, v17
	v_cvt_pk_bf16_f32 v17, v18, v19
	v_cvt_pk_bf16_f32 v18, v12, v13
	v_cvt_pk_bf16_f32 v19, v14, v15
	v_add_u32_e32 v226, 0x58000, v2
	global_store_dwordx4 v226, v[16:19], s[46:47] offset:0
	s_waitcnt vmcnt(6)
	v_lshlrev_b32_e32 v220, 16, v152
	v_and_b32_e32 v221, 0xffff0000, v152
	v_pk_mul_f32 v[8:9], v[8:9], v[220:221]
	v_lshlrev_b32_e32 v222, 16, v153
	v_and_b32_e32 v223, 0xffff0000, v153
	v_pk_mul_f32 v[10:11], v[10:11], v[222:223]
	v_lshlrev_b32_e32 v224, 16, v154
	v_and_b32_e32 v225, 0xffff0000, v154
	v_pk_mul_f32 v[4:5], v[4:5], v[224:225]
	v_lshlrev_b32_e32 v220, 16, v155
	v_and_b32_e32 v221, 0xffff0000, v155
	v_pk_mul_f32 v[6:7], v[6:7], v[220:221]
	v_lshlrev_b32_e32 v220, 16, v156
	v_and_b32_e32 v221, 0xffff0000, v156
	v_pk_add_f32 v[8:9], v[8:9], v[220:221]
	v_lshlrev_b32_e32 v222, 16, v157
	v_and_b32_e32 v223, 0xffff0000, v157
	v_pk_add_f32 v[10:11], v[10:11], v[222:223]
	v_lshlrev_b32_e32 v224, 16, v158
	v_and_b32_e32 v225, 0xffff0000, v158
	v_pk_add_f32 v[4:5], v[4:5], v[224:225]
	v_lshlrev_b32_e32 v220, 16, v159
	v_and_b32_e32 v221, 0xffff0000, v159
	v_pk_add_f32 v[6:7], v[6:7], v[220:221]
	v_cvt_pk_bf16_f32 v8, v8, v9
	v_cvt_pk_bf16_f32 v9, v10, v11
	v_cvt_pk_bf16_f32 v10, v4, v5
	v_cvt_pk_bf16_f32 v11, v6, v7
	v_add_u32_e32 v226, 0x58000, v2
	global_store_dwordx4 v226, v[8:11], s[46:47] offset:256
	s_branch .Le5_done
; __device__ __forceinline__ float sigmoid_f(float x) { return __builtin_amdgcn_rcpf(1.f + __builtin_amdgcn_exp2f(-1.4426950408889634f * x)); }
; __device__ __forceinline__ float bf_lo(unsigned u) { return __uint_as_float(u << 16); }
; __device__ __forceinline__ float bf_hi(unsigned u) { return __uint_as_float(u & 0xffff0000u); }
; __device__ __forceinline__ u32x4 pack8(const f32x4 v0, const f32x4 v1) { u32x4 w; w.x = cvt_pk_bf16(v0[0], v0[1]); w.y = cvt_pk_bf16(v0[2], v0[3]); w.z = cvt_pk_bf16(v1[0], v1[1]); w.w = cvt_pk_bf16(v1[2], v1[3]); return w; }
;     __device__ __forceinline__ void operator()(const f32x4 (&acc)[2][2][4][2], const Unit& u, int wr, int wc, int fr, int fq) const {
;     ...
;                     for (int bj = 0; bj < 2; ++bj) { f32x4 v0 = acc[ai][bj][m][0], v1 = acc[ai][bj][m][1]; bf16_t* p = ob + (unsigned)(r * ld + col0 + bj * HALF);
;                         if constexpr (MODE == 0) { v0 = v0 * sc; v1 = v1 * sc; }
;                         if constexpr (MODE == 3) { v0 = (v0 + bv[bj][0]) * sv[bj][0]; v1 = (v1 + bv[bj][1]) * sv[bj][1]; }
;                         if constexpr (MODE == 4) {
; #pragma unroll
;                             for (int e = 0; e < 4; ++e) { v0[e] = sigmoid_f(v0[e] * sc); v1[e] = sigmoid_f(v1[e] * sc); } }
;                         if constexpr (MODE == 5) { const u32x4 g = *(const u32x4*)(G + (unsigned)(r * ld + col0 + bj * HALF));
;                             v0 = v0 * (f32x4){bf_lo(g.x), bf_hi(g.x), bf_lo(g.y), bf_hi(g.y)}; v1 = v1 * (f32x4){bf_lo(g.z), bf_hi(g.z), bf_lo(g.w), bf_hi(g.w)};
;                             if (!first) { const u32x4 q = *(const u32x4*)p; v0 = v0 + (f32x4){bf_lo(q.x), bf_hi(q.x), bf_lo(q.y), bf_hi(q.y)}; v1 = v1 + (f32x4){bf_lo(q.z), bf_hi(q.z), bf_lo(q.w), bf_hi(q.w)}; } }
;                         *(u32x4*)p = pack8(v0, v1); }
.Le5_first:
	v_add_u32_e32 v226, 0x0, v2
	global_load_dwordx4 v[142:145], v226, s[50:51] offset:0
	v_add_u32_e32 v226, 0x0, v2
	global_load_dwordx4 v[148:151], v226, s[50:51] offset:256
	v_add_u32_e32 v226, 0x8000, v2
	global_load_dwordx4 v[152:155], v226, s[50:51] offset:0
	v_add_u32_e32 v226, 0x8000, v2
	global_load_dwordx4 v[156:159], v226, s[50:51] offset:256
	v_add_u32_e32 v226, 0x10000, v2
	global_load_dwordx4 v[160:163], v226, s[50:51] offset:0
	v_add_u32_e32 v226, 0x10000, v2
	global_load_dwordx4 v[164:167], v226, s[50:51] offset:256
	v_add_u32_e32 v226, 0x18000, v2
	global_load_dwordx4 v[168:171], v226, s[50:51] offset:0
	v_add_u32_e32 v226, 0x18000, v2
	global_load_dwordx4 v[172:175], v226, s[50:51] offset:256
	v_add_u32_e32 v226, 0x40000, v2
	global_load_dwordx4 v[176:179], v226, s[50:51] offset:0
	v_add_u32_e32 v226, 0x40000, v2
	global_load_dwordx4 v[180:183], v226, s[50:51] offset:256
	v_add_u32_e32 v226, 0x48000, v2
	global_load_dwordx4 v[194:197], v226, s[50:51] offset:0
	v_add_u32_e32 v226, 0x48000, v2
	global_load_dwordx4 v[198:201], v226, s[50:51] offset:256
	v_add_u32_e32 v226, 0x50000, v2
	global_load_dwordx4 v[202:205], v226, s[50:51] offset:0
	v_add_u32_e32 v226, 0x50000, v2
	global_load_dwordx4 v[206:209], v226, s[50:51] offset:256
	s_waitcnt vmcnt(13)
	v_lshlrev_b32_e32 v220, 16, v142
	v_and_b32_e32 v221, 0xffff0000, v142
	v_pk_mul_f32 v[128:129], v[128:129], v[220:221]
	v_lshlrev_b32_e32 v222, 16, v143
	v_and_b32_e32 v223, 0xffff0000, v143
	v_pk_mul_f32 v[130:131], v[130:131], v[222:223]
	v_lshlrev_b32_e32 v224, 16, v144
	v_and_b32_e32 v225, 0xffff0000, v144
	v_pk_mul_f32 v[124:125], v[124:125], v[224:225]
	v_lshlrev_b32_e32 v220, 16, v145
	v_and_b32_e32 v221, 0xffff0000, v145
	v_pk_mul_f32 v[126:127], v[126:127], v[220:221]
	v_cvt_pk_bf16_f32 v128, v128, v129
	v_cvt_pk_bf16_f32 v129, v130, v131
	v_cvt_pk_bf16_f32 v130, v124, v125
	v_cvt_pk_bf16_f32 v131, v126, v127
	v_add_u32_e32 v226, 0x0, v2
	global_store_dwordx4 v226, v[128:131], s[46:47] offset:0
	v_add_u32_e32 v226, 0x58000, v2
	global_load_dwordx4 v[142:145], v226, s[50:51] offset:0
	s_waitcnt vmcnt(14)
	v_lshlrev_b32_e32 v220, 16, v148
	v_and_b32_e32 v221, 0xffff0000, v148
	v_pk_mul_f32 v[120:121], v[120:121], v[220:221]
	v_lshlrev_b32_e32 v222, 16, v149
	v_and_b32_e32 v223, 0xffff0000, v149
	v_pk_mul_f32 v[122:123], v[122:123], v[222:223]
	v_lshlrev_b32_e32 v224, 16, v150
	v_and_b32_e32 v225, 0xffff0000, v150
	v_pk_mul_f32 v[116:117], v[116:117], v[224:225]
	v_lshlrev_b32_e32 v220, 16, v151
	v_and_b32_e32 v221, 0xffff0000, v151
	v_pk_mul_f32 v[118:119], v[118:119], v[220:221]
	v_cvt_pk_bf16_f32 v120, v120, v121
	v_cvt_pk_bf16_f32 v121, v122, v123
	v_cvt_pk_bf16_f32 v122, v116, v117
	v_cvt_pk_bf16_f32 v123, v118, v119
	v_add_u32_e32 v226, 0x0, v2
	global_store_dwordx4 v226, v[120:123], s[46:47] offset:256
	v_add_u32_e32 v226, 0x58000, v2
	global_load_dwordx4 v[148:151], v226, s[50:51] offset:256
	s_waitcnt vmcnt(15)
	v_lshlrev_b32_e32 v220, 16, v152
	v_and_b32_e32 v221, 0xffff0000, v152
	v_pk_mul_f32 v[112:113], v[112:113], v[220:221]
	v_lshlrev_b32_e32 v222, 16, v153
	v_and_b32_e32 v223, 0xffff0000, v153
	v_pk_mul_f32 v[114:115], v[114:115], v[222:223]
	v_lshlrev_b32_e32 v224, 16, v154
	v_and_b32_e32 v225, 0xffff0000, v154
	v_pk_mul_f32 v[108:109], v[108:109], v[224:225]
	v_lshlrev_b32_e32 v220, 16, v155
	v_and_b32_e32 v221, 0xffff0000, v155
	v_pk_mul_f32 v[110:111], v[110:111], v[220:221]
	v_cvt_pk_bf16_f32 v112, v112, v113
	v_cvt_pk_bf16_f32 v113, v114, v115
	v_cvt_pk_bf16_f32 v114, v108, v109
	v_cvt_pk_bf16_f32 v115, v110, v111
	v_add_u32_e32 v226, 0x8000, v2
	global_store_dwordx4 v226, v[112:115], s[46:47] offset:0
	s_waitcnt vmcnt(15)
	v_lshlrev_b32_e32 v220, 16, v156
	v_and_b32_e32 v221, 0xffff0000, v156
	v_pk_mul_f32 v[104:105], v[104:105], v[220:221]
	v_lshlrev_b32_e32 v222, 16, v157
	v_and_b32_e32 v223, 0xffff0000, v157
	v_pk_mul_f32 v[106:107], v[106:107], v[222:223]
	v_lshlrev_b32_e32 v224, 16, v158
	v_and_b32_e32 v225, 0xffff0000, v158
	v_pk_mul_f32 v[100:101], v[100:101], v[224:225]
	v_lshlrev_b32_e32 v220, 16, v159
	v_and_b32_e32 v221, 0xffff0000, v159
	v_pk_mul_f32 v[102:103], v[102:103], v[220:221]
	v_cvt_pk_bf16_f32 v104, v104, v105
	v_cvt_pk_bf16_f32 v105, v106, v107
	v_cvt_pk_bf16_f32 v106, v100, v101
	v_cvt_pk_bf16_f32 v107, v102, v103
	v_add_u32_e32 v226, 0x8000, v2
	global_store_dwordx4 v226, v[104:107], s[46:47] offset:256
	s_waitcnt vmcnt(15)
	v_lshlrev_b32_e32 v220, 16, v160
	v_and_b32_e32 v221, 0xffff0000, v160
	v_pk_mul_f32 v[96:97], v[96:97], v[220:221]
	v_lshlrev_b32_e32 v222, 16, v161
	v_and_b32_e32 v223, 0xffff0000, v161
	v_pk_mul_f32 v[98:99], v[98:99], v[222:223]
	v_lshlrev_b32_e32 v224, 16, v162
	v_and_b32_e32 v225, 0xffff0000, v162
	v_pk_mul_f32 v[92:93], v[92:93], v[224:225]
	v_lshlrev_b32_e32 v220, 16, v163
	v_and_b32_e32 v221, 0xffff0000, v163
	v_pk_mul_f32 v[94:95], v[94:95], v[220:221]
	v_cvt_pk_bf16_f32 v96, v96, v97
	v_cvt_pk_bf16_f32 v97, v98, v99
	v_cvt_pk_bf16_f32 v98, v92, v93
	v_cvt_pk_bf16_f32 v99, v94, v95
	v_add_u32_e32 v226, 0x10000, v2
	global_store_dwordx4 v226, v[96:99], s[46:47] offset:0
	s_waitcnt vmcnt(15)
	v_lshlrev_b32_e32 v220, 16, v164
	v_and_b32_e32 v221, 0xffff0000, v164
	v_pk_mul_f32 v[88:89], v[88:89], v[220:221]
	v_lshlrev_b32_e32 v222, 16, v165
	v_and_b32_e32 v223, 0xffff0000, v165
	v_pk_mul_f32 v[90:91], v[90:91], v[222:223]
	v_lshlrev_b32_e32 v224, 16, v166
	v_and_b32_e32 v225, 0xffff0000, v166
	v_pk_mul_f32 v[84:85], v[84:85], v[224:225]
	v_lshlrev_b32_e32 v220, 16, v167
	v_and_b32_e32 v221, 0xffff0000, v167
	v_pk_mul_f32 v[86:87], v[86:87], v[220:221]
	v_cvt_pk_bf16_f32 v88, v88, v89
	v_cvt_pk_bf16_f32 v89, v90, v91
	v_cvt_pk_bf16_f32 v90, v84, v85
	v_cvt_pk_bf16_f32 v91, v86, v87
	v_add_u32_e32 v226, 0x10000, v2
	global_store_dwordx4 v226, v[88:91], s[46:47] offset:256
	s_waitcnt vmcnt(15)
; __device__ __forceinline__ float sigmoid_f(float x) { return __builtin_amdgcn_rcpf(1.f + __builtin_amdgcn_exp2f(-1.4426950408889634f * x)); }
; __device__ __forceinline__ float bf_lo(unsigned u) { return __uint_as_float(u << 16); }
; __device__ __forceinline__ float bf_hi(unsigned u) { return __uint_as_float(u & 0xffff0000u); }
; __device__ __forceinline__ u32x4 pack8(const f32x4 v0, const f32x4 v1) { u32x4 w; w.x = cvt_pk_bf16(v0[0], v0[1]); w.y = cvt_pk_bf16(v0[2], v0[3]); w.z = cvt_pk_bf16(v1[0], v1[1]); w.w = cvt_pk_bf16(v1[2], v1[3]); return w; }
;     __device__ __forceinline__ void operator()(const f32x4 (&acc)[2][2][4][2], const Unit& u, int wr, int wc, int fr, int fq) const {
;     ...
;                     for (int bj = 0; bj < 2; ++bj) { f32x4 v0 = acc[ai][bj][m][0], v1 = acc[ai][bj][m][1]; bf16_t* p = ob + (unsigned)(r * ld + col0 + bj * HALF);
;                         if constexpr (MODE == 0) { v0 = v0 * sc; v1 = v1 * sc; }
;                         if constexpr (MODE == 3) { v0 = (v0 + bv[bj][0]) * sv[bj][0]; v1 = (v1 + bv[bj][1]) * sv[bj][1]; }
;                         if constexpr (MODE == 4) {
; #pragma unroll
;                             for (int e = 0; e < 4; ++e) { v0[e] = sigmoid_f(v0[e] * sc); v1[e] = sigmoid_f(v1[e] * sc); } }
;                         if constexpr (MODE == 5) { const u32x4 g = *(const u32x4*)(G + (unsigned)(r * ld + col0 + bj * HALF));
;                             v0 = v0 * (f32x4){bf_lo(g.x), bf_hi(g.x), bf_lo(g.y), bf_hi(g.y)}; v1 = v1 * (f32x4){bf_lo(g.z), bf_hi(g.z), bf_lo(g.w), bf_hi(g.w)};
;                             if (!first) { const u32x4 q = *(const u32x4*)p; v0 = v0 + (f32x4){bf_lo(q.x), bf_hi(q.x), bf_lo(q.y), bf_hi(q.y)}; v1 = v1 + (f32x4){bf_lo(q.z), bf_hi(q.z), bf_lo(q.w), bf_hi(q.w)}; } }
;                         *(u32x4*)p = pack8(v0, v1); }
	v_lshlrev_b32_e32 v220, 16, v168
	v_and_b32_e32 v221, 0xffff0000, v168
	v_pk_mul_f32 v[80:81], v[80:81], v[220:221]
	v_lshlrev_b32_e32 v222, 16, v169
	v_and_b32_e32 v223, 0xffff0000, v169
	v_pk_mul_f32 v[82:83], v[82:83], v[222:223]
	v_lshlrev_b32_e32 v224, 16, v170
	v_and_b32_e32 v225, 0xffff0000, v170
	v_pk_mul_f32 v[76:77], v[76:77], v[224:225]
	v_lshlrev_b32_e32 v220, 16, v171
	v_and_b32_e32 v221, 0xffff0000, v171
	v_pk_mul_f32 v[78:79], v[78:79], v[220:221]
	v_cvt_pk_bf16_f32 v80, v80, v81
	v_cvt_pk_bf16_f32 v81, v82, v83
	v_cvt_pk_bf16_f32 v82, v76, v77
	v_cvt_pk_bf16_f32 v83, v78, v79
	v_add_u32_e32 v226, 0x18000, v2
	global_store_dwordx4 v226, v[80:83], s[46:47] offset:0
	s_waitcnt vmcnt(15)
	v_lshlrev_b32_e32 v220, 16, v172
	v_and_b32_e32 v221, 0xffff0000, v172
	v_pk_mul_f32 v[72:73], v[72:73], v[220:221]
	v_lshlrev_b32_e32 v222, 16, v173
	v_and_b32_e32 v223, 0xffff0000, v173
	v_pk_mul_f32 v[74:75], v[74:75], v[222:223]
	v_lshlrev_b32_e32 v224, 16, v174
	v_and_b32_e32 v225, 0xffff0000, v174
	v_pk_mul_f32 v[68:69], v[68:69], v[224:225]
	v_lshlrev_b32_e32 v220, 16, v175
	v_and_b32_e32 v221, 0xffff0000, v175
	v_pk_mul_f32 v[70:71], v[70:71], v[220:221]
	v_cvt_pk_bf16_f32 v72, v72, v73
	v_cvt_pk_bf16_f32 v73, v74, v75
	v_cvt_pk_bf16_f32 v74, v68, v69
	v_cvt_pk_bf16_f32 v75, v70, v71
	v_add_u32_e32 v226, 0x18000, v2
	global_store_dwordx4 v226, v[72:75], s[46:47] offset:256
	s_waitcnt vmcnt(15)
	v_lshlrev_b32_e32 v220, 16, v176
	v_and_b32_e32 v221, 0xffff0000, v176
	v_pk_mul_f32 v[64:65], v[64:65], v[220:221]
	v_lshlrev_b32_e32 v222, 16, v177
	v_and_b32_e32 v223, 0xffff0000, v177
	v_pk_mul_f32 v[66:67], v[66:67], v[222:223]
	v_lshlrev_b32_e32 v224, 16, v178
	v_and_b32_e32 v225, 0xffff0000, v178
	v_pk_mul_f32 v[60:61], v[60:61], v[224:225]
	v_lshlrev_b32_e32 v220, 16, v179
	v_and_b32_e32 v221, 0xffff0000, v179
	v_pk_mul_f32 v[62:63], v[62:63], v[220:221]
	v_cvt_pk_bf16_f32 v64, v64, v65
	v_cvt_pk_bf16_f32 v65, v66, v67
	v_cvt_pk_bf16_f32 v66, v60, v61
	v_cvt_pk_bf16_f32 v67, v62, v63
	v_add_u32_e32 v226, 0x40000, v2
	global_store_dwordx4 v226, v[64:67], s[46:47] offset:0
	s_waitcnt vmcnt(15)
	v_lshlrev_b32_e32 v220, 16, v180
	v_and_b32_e32 v221, 0xffff0000, v180
	v_pk_mul_f32 v[56:57], v[56:57], v[220:221]
	v_lshlrev_b32_e32 v222, 16, v181
	v_and_b32_e32 v223, 0xffff0000, v181
	v_pk_mul_f32 v[58:59], v[58:59], v[222:223]
	v_lshlrev_b32_e32 v224, 16, v182
	v_and_b32_e32 v225, 0xffff0000, v182
	v_pk_mul_f32 v[52:53], v[52:53], v[224:225]
	v_lshlrev_b32_e32 v220, 16, v183
	v_and_b32_e32 v221, 0xffff0000, v183
	v_pk_mul_f32 v[54:55], v[54:55], v[220:221]
	v_cvt_pk_bf16_f32 v56, v56, v57
	v_cvt_pk_bf16_f32 v57, v58, v59
	v_cvt_pk_bf16_f32 v58, v52, v53
	v_cvt_pk_bf16_f32 v59, v54, v55
	v_add_u32_e32 v226, 0x40000, v2
	global_store_dwordx4 v226, v[56:59], s[46:47] offset:256
	s_waitcnt vmcnt(15)
	v_lshlrev_b32_e32 v220, 16, v194
	v_and_b32_e32 v221, 0xffff0000, v194
	v_pk_mul_f32 v[48:49], v[48:49], v[220:221]
	v_lshlrev_b32_e32 v222, 16, v195
	v_and_b32_e32 v223, 0xffff0000, v195
	v_pk_mul_f32 v[50:51], v[50:51], v[222:223]
	v_lshlrev_b32_e32 v224, 16, v196
	v_and_b32_e32 v225, 0xffff0000, v196
	v_pk_mul_f32 v[44:45], v[44:45], v[224:225]
	v_lshlrev_b32_e32 v220, 16, v197
	v_and_b32_e32 v221, 0xffff0000, v197
	v_pk_mul_f32 v[46:47], v[46:47], v[220:221]
	v_cvt_pk_bf16_f32 v48, v48, v49
	v_cvt_pk_bf16_f32 v49, v50, v51
	v_cvt_pk_bf16_f32 v50, v44, v45
	v_cvt_pk_bf16_f32 v51, v46, v47
	v_add_u32_e32 v226, 0x48000, v2
	global_store_dwordx4 v226, v[48:51], s[46:47] offset:0
	s_waitcnt vmcnt(15)
; __device__ __forceinline__ float sigmoid_f(float x) { return __builtin_amdgcn_rcpf(1.f + __builtin_amdgcn_exp2f(-1.4426950408889634f * x)); }
; __device__ __forceinline__ float bf_lo(unsigned u) { return __uint_as_float(u << 16); }
; __device__ __forceinline__ float bf_hi(unsigned u) { return __uint_as_float(u & 0xffff0000u); }
; __device__ __forceinline__ u32x4 pack8(const f32x4 v0, const f32x4 v1) { u32x4 w; w.x = cvt_pk_bf16(v0[0], v0[1]); w.y = cvt_pk_bf16(v0[2], v0[3]); w.z = cvt_pk_bf16(v1[0], v1[1]); w.w = cvt_pk_bf16(v1[2], v1[3]); return w; }
;     __device__ __forceinline__ void operator()(const f32x4 (&acc)[2][2][4][2], const Unit& u, int wr, int wc, int fr, int fq) const {
;     ...
;                     for (int bj = 0; bj < 2; ++bj) { f32x4 v0 = acc[ai][bj][m][0], v1 = acc[ai][bj][m][1]; bf16_t* p = ob + (unsigned)(r * ld + col0 + bj * HALF);
;                         if constexpr (MODE == 0) { v0 = v0 * sc; v1 = v1 * sc; }
;                         if constexpr (MODE == 3) { v0 = (v0 + bv[bj][0]) * sv[bj][0]; v1 = (v1 + bv[bj][1]) * sv[bj][1]; }
;                         if constexpr (MODE == 4) {
; #pragma unroll
;                             for (int e = 0; e < 4; ++e) { v0[e] = sigmoid_f(v0[e] * sc); v1[e] = sigmoid_f(v1[e] * sc); } }
;                         if constexpr (MODE == 5) { const u32x4 g = *(const u32x4*)(G + (unsigned)(r * ld + col0 + bj * HALF));
;                             v0 = v0 * (f32x4){bf_lo(g.x), bf_hi(g.x), bf_lo(g.y), bf_hi(g.y)}; v1 = v1 * (f32x4){bf_lo(g.z), bf_hi(g.z), bf_lo(g.w), bf_hi(g.w)};
;                             if (!first) { const u32x4 q = *(const u32x4*)p; v0 = v0 + (f32x4){bf_lo(q.x), bf_hi(q.x), bf_lo(q.y), bf_hi(q.y)}; v1 = v1 + (f32x4){bf_lo(q.z), bf_hi(q.z), bf_lo(q.w), bf_hi(q.w)}; } }
;                         *(u32x4*)p = pack8(v0, v1); }
	v_lshlrev_b32_e32 v220, 16, v198
	v_and_b32_e32 v221, 0xffff0000, v198
	v_pk_mul_f32 v[40:41], v[40:41], v[220:221]
	v_lshlrev_b32_e32 v222, 16, v199
	v_and_b32_e32 v223, 0xffff0000, v199
	v_pk_mul_f32 v[42:43], v[42:43], v[222:223]
	v_lshlrev_b32_e32 v224, 16, v200
	v_and_b32_e32 v225, 0xffff0000, v200
	v_pk_mul_f32 v[36:37], v[36:37], v[224:225]
	v_lshlrev_b32_e32 v220, 16, v201
	v_and_b32_e32 v221, 0xffff0000, v201
	v_pk_mul_f32 v[38:39], v[38:39], v[220:221]
	v_cvt_pk_bf16_f32 v40, v40, v41
	v_cvt_pk_bf16_f32 v41, v42, v43
	v_cvt_pk_bf16_f32 v42, v36, v37
	v_cvt_pk_bf16_f32 v43, v38, v39
	v_add_u32_e32 v226, 0x48000, v2
	global_store_dwordx4 v226, v[40:43], s[46:47] offset:256
	s_waitcnt vmcnt(15)
	v_lshlrev_b32_e32 v220, 16, v202
	v_and_b32_e32 v221, 0xffff0000, v202
	v_pk_mul_f32 v[32:33], v[32:33], v[220:221]
	v_lshlrev_b32_e32 v222, 16, v203
	v_and_b32_e32 v223, 0xffff0000, v203
	v_pk_mul_f32 v[34:35], v[34:35], v[222:223]
	v_lshlrev_b32_e32 v224, 16, v204
	v_and_b32_e32 v225, 0xffff0000, v204
	v_pk_mul_f32 v[28:29], v[28:29], v[224:225]
	v_lshlrev_b32_e32 v220, 16, v205
	v_and_b32_e32 v221, 0xffff0000, v205
	v_pk_mul_f32 v[30:31], v[30:31], v[220:221]
	v_cvt_pk_bf16_f32 v32, v32, v33
	v_cvt_pk_bf16_f32 v33, v34, v35
	v_cvt_pk_bf16_f32 v34, v28, v29
	v_cvt_pk_bf16_f32 v35, v30, v31
	v_add_u32_e32 v226, 0x50000, v2
	global_store_dwordx4 v226, v[32:35], s[46:47] offset:0
	s_waitcnt vmcnt(15)
	v_lshlrev_b32_e32 v220, 16, v206
	v_and_b32_e32 v221, 0xffff0000, v206
	v_pk_mul_f32 v[24:25], v[24:25], v[220:221]
	v_lshlrev_b32_e32 v222, 16, v207
	v_and_b32_e32 v223, 0xffff0000, v207
	v_pk_mul_f32 v[26:27], v[26:27], v[222:223]
	v_lshlrev_b32_e32 v224, 16, v208
	v_and_b32_e32 v225, 0xffff0000, v208
	v_pk_mul_f32 v[20:21], v[20:21], v[224:225]
	v_lshlrev_b32_e32 v220, 16, v209
	v_and_b32_e32 v221, 0xffff0000, v209
	v_pk_mul_f32 v[22:23], v[22:23], v[220:221]
	v_cvt_pk_bf16_f32 v24, v24, v25
	v_cvt_pk_bf16_f32 v25, v26, v27
	v_cvt_pk_bf16_f32 v26, v20, v21
	v_cvt_pk_bf16_f32 v27, v22, v23
	v_add_u32_e32 v226, 0x50000, v2
	global_store_dwordx4 v226, v[24:27], s[46:47] offset:256
	s_waitcnt vmcnt(14)
	v_lshlrev_b32_e32 v220, 16, v142
	v_and_b32_e32 v221, 0xffff0000, v142
	v_pk_mul_f32 v[16:17], v[16:17], v[220:221]
	v_lshlrev_b32_e32 v222, 16, v143
	v_and_b32_e32 v223, 0xffff0000, v143
	v_pk_mul_f32 v[18:19], v[18:19], v[222:223]
	v_lshlrev_b32_e32 v224, 16, v144
	v_and_b32_e32 v225, 0xffff0000, v144
	v_pk_mul_f32 v[12:13], v[12:13], v[224:225]
	v_lshlrev_b32_e32 v220, 16, v145
	v_and_b32_e32 v221, 0xffff0000, v145
	v_pk_mul_f32 v[14:15], v[14:15], v[220:221]
	v_cvt_pk_bf16_f32 v16, v16, v17
	v_cvt_pk_bf16_f32 v17, v18, v19
	v_cvt_pk_bf16_f32 v18, v12, v13
	v_cvt_pk_bf16_f32 v19, v14, v15
	v_add_u32_e32 v226, 0x58000, v2
	global_store_dwordx4 v226, v[16:19], s[46:47] offset:0
	s_waitcnt vmcnt(13)
	v_lshlrev_b32_e32 v220, 16, v148
	v_and_b32_e32 v221, 0xffff0000, v148
	v_pk_mul_f32 v[8:9], v[8:9], v[220:221]
	v_lshlrev_b32_e32 v222, 16, v149
	v_and_b32_e32 v223, 0xffff0000, v149
	v_pk_mul_f32 v[10:11], v[10:11], v[222:223]
	v_lshlrev_b32_e32 v224, 16, v150
	v_and_b32_e32 v225, 0xffff0000, v150
	v_pk_mul_f32 v[4:5], v[4:5], v[224:225]
	v_lshlrev_b32_e32 v220, 16, v151
	v_and_b32_e32 v221, 0xffff0000, v151
	v_pk_mul_f32 v[6:7], v[6:7], v[220:221]
	v_cvt_pk_bf16_f32 v8, v8, v9
	v_cvt_pk_bf16_f32 v9, v10, v11
	v_cvt_pk_bf16_f32 v10, v4, v5
	v_cvt_pk_bf16_f32 v11, v6, v7
	v_add_u32_e32 v226, 0x58000, v2
	global_store_dwordx4 v226, v[8:11], s[46:47] offset:256

; __device__ __forceinline__ float bf_lo(unsigned u) { return __uint_as_float(u << 16); }
; __device__ __forceinline__ float bf_hi(unsigned u) { return __uint_as_float(u & 0xffff0000u); }
; __device__ __forceinline__ u32x4 pack8(const f32x4 v0, const f32x4 v1) { u32x4 w; w.x = cvt_pk_bf16(v0[0], v0[1]); w.y = cvt_pk_bf16(v0[2], v0[3]); w.z = cvt_pk_bf16(v1[0], v1[1]); w.w = cvt_pk_bf16(v1[2], v1[3]); return w; }
;     __device__ __forceinline__ void operator()(const f32x4 (&acc)[2][2][4][2], const Unit& u, int wr, int wc, int fr, int fq) const {
;     ...
;                 for (int m = 0; m < 4; ++m) { const int r = row0 + ai * HALF + m * 16; float s = 0.f;
; #pragma unroll
;                     for (int bj = 0; bj < 2; ++bj) { const unsigned off = (unsigned)(r * 1024 + u.pn * BM + bj * HALF + wc * 32 + 8 * fq);
;                         const u32x4 bq = *(const u32x4*)(O + off);
;                         const f32x4 b0 = {bf_lo(bq.x), bf_hi(bq.x), bf_lo(bq.y), bf_hi(bq.y)}, b1 = {bf_lo(bq.z), bf_hi(bq.z), bf_lo(bq.w), bf_hi(bq.w)};
;                         const f32x4 h0 = b0 + acc[ai][bj][m][0] * alpha, h1 = b1 + acc[ai][bj][m][1] * alpha;
;                         *(u32x4*)(O + off) = pack8(h0, h1);
;                         s += (h0[0] * h0[0] + h0[1] * h0[1]) + (h0[2] * h0[2] + h0[3] * h0[3]) + (h1[0] * h1[0] + h1[1] * h1[1]) + (h1[2] * h1[2] + h1[3] * h1[3]); }
;                     s += __shfl_xor(s, 16); s += __shfl_xor(s, 32);
;                     if (fq == 0) ssq_out[(unsigned)(r * 16 + u.pn * 4 + wc)] = s;
;                     asm volatile("" ::: "memory"); }
.LBB0_533:
	s_mov_b64 s[58:59], s[48:49]
	s_mov_b64 s[62:63], s[34:35]
	s_mov_b64 s[26:27], 0
	s_mov_b64 s[38:39], 0
	s_mov_b64 s[50:51], 0
	s_mov_b64 s[60:61], 0
	s_mov_b32 s20, s7
	s_mov_b64 s[26:27], 0
	s_mov_b64 s[38:39], 0
	s_mov_b64 s[50:51], 0
	s_mov_b32 s60, s6
	v_mov_b32_e32 v2, v184
	s_lshl_b32 s5, s5, 8
	s_add_i32 s5, s5, s70
	v_and_b32_e32 v143, 64, v216
	v_bfe_u32 v142, v2, 4, 2
	v_and_or_b32 v148, v2, 15, s5
	v_xor_b32_e32 v2, 16, v216
	v_add_u32_e32 v143, 64, v143
	v_cmp_lt_i32_e32 vcc, v2, v143
	s_lshl_b32 s5, s4, 8
	s_or_b32 s5, s5, s71
	v_cndmask_b32_e32 v2, v216, v2, vcc
	v_lshlrev_b32_e32 v147, 2, v2
	v_xor_b32_e32 v2, 32, v216
	v_cmp_lt_i32_e32 vcc, v2, v143
	v_lshl_or_b32 v149, v142, 3, s5
	s_lshl_b32 s4, s4, 2
	v_cndmask_b32_e32 v2, v216, v2, vcc
	v_lshlrev_b32_e32 v146, 2, v2
	v_lshl_add_u32 v2, v148, 10, v149
	v_lshlrev_b32_e32 v230, 1, v2
	v_add_u32_e32 v231, 0x0, v230
	global_load_dwordx4 v[158:161], v231, s[62:63] offset:0
	v_add_u32_e32 v231, 0x0, v230
	global_load_dwordx4 v[162:165], v231, s[62:63] offset:256
	v_add_u32_e32 v231, 0x8000, v230
	global_load_dwordx4 v[166:169], v231, s[62:63] offset:0
	v_add_u32_e32 v231, 0x8000, v230
	global_load_dwordx4 v[170:173], v231, s[62:63] offset:256
	v_add_u32_e32 v231, 0x10000, v230
	global_load_dwordx4 v[174:177], v231, s[62:63] offset:0
	v_add_u32_e32 v231, 0x10000, v230
	global_load_dwordx4 v[178:181], v231, s[62:63] offset:256
	v_add_u32_e32 v231, 0x18000, v230
	global_load_dwordx4 v[194:197], v231, s[62:63] offset:0
	v_add_u32_e32 v231, 0x18000, v230
	global_load_dwordx4 v[198:201], v231, s[62:63] offset:256
	v_add_u32_e32 v231, 0x40000, v230
	global_load_dwordx4 v[202:205], v231, s[62:63] offset:0
	v_add_u32_e32 v231, 0x40000, v230
	global_load_dwordx4 v[206:209], v231, s[62:63] offset:256
	v_add_u32_e32 v231, 0x48000, v230
	global_load_dwordx4 v[220:223], v231, s[62:63] offset:0
	v_add_u32_e32 v231, 0x48000, v230
	global_load_dwordx4 v[224:227], v231, s[62:63] offset:256
	v_cmp_eq_u32_e32 vcc, 0, v142
	v_lshl_add_u64 v[142:143], v[2:3], 1, s[62:63]
	s_waitcnt vmcnt(11)
	v_mov_b32_e32 v150, v158
	v_mov_b32_e32 v151, v159
	v_mov_b32_e32 v152, v160
	v_mov_b32_e32 v153, v161
	v_add_u32_e32 v231, 0x50000, v230
	global_load_dwordx4 v[158:161], v231, s[62:63] offset:0
	s_or_b32 s4, s4, s67
	s_waitcnt lgkmcnt(0)
	v_lshlrev_b32_e32 v154, 16, v150
	v_and_b32_e32 v155, 0xffff0000, v150
	v_lshlrev_b32_e32 v150, 16, v151
	v_and_b32_e32 v151, 0xffff0000, v151
	v_lshlrev_b32_e32 v156, 16, v152
	v_and_b32_e32 v157, 0xffff0000, v152
	v_lshlrev_b32_e32 v152, 16, v153
	v_and_b32_e32 v153, 0xffff0000, v153
	v_pk_fma_f32 v[150:151], v[126:127], s[60:61], v[150:151] op_sel_hi:[1,0,1]
	v_pk_fma_f32 v[154:155], v[124:125], s[60:61], v[154:155] op_sel_hi:[1,0,1]
	v_pk_fma_f32 v[130:131], v[130:131], s[60:61], v[152:153] op_sel_hi:[1,0,1]
	v_pk_fma_f32 v[128:129], v[128:129], s[60:61], v[156:157] op_sel_hi:[1,0,1]
	v_cvt_pk_bf16_f32 v124, v154, v155
	v_cvt_pk_bf16_f32 v125, v150, v151
	v_cvt_pk_bf16_f32 v126, v128, v129
	v_cvt_pk_bf16_f32 v127, v130, v131
	global_store_dwordx4 v[142:143], v[124:127], off
	v_mul_f32_e32 v2, v155, v155
	v_fmac_f32_e32 v2, v154, v154
	v_mul_f32_e32 v124, v151, v151
	v_fmac_f32_e32 v124, v150, v150
	v_add_f32_e32 v2, v2, v124
	v_mul_f32_e32 v124, v129, v129
	v_fmac_f32_e32 v124, v128, v128
	v_add_f32_e32 v2, v124, v2
	v_mul_f32_e32 v124, v131, v131
	v_fmac_f32_e32 v124, v130, v130
	v_add_f32_e32 v2, v124, v2
	s_waitcnt vmcnt(12)
	v_mov_b32_e32 v124, v162
	v_mov_b32_e32 v125, v163
	v_mov_b32_e32 v126, v164
	v_mov_b32_e32 v127, v165
	v_add_u32_e32 v231, 0x50000, v230
	global_load_dwordx4 v[162:165], v231, s[62:63] offset:256
	s_waitcnt lgkmcnt(0)
	v_lshlrev_b32_e32 v128, 16, v124
	v_and_b32_e32 v129, 0xffff0000, v124
	v_lshlrev_b32_e32 v124, 16, v125
	v_and_b32_e32 v125, 0xffff0000, v125
	v_lshlrev_b32_e32 v130, 16, v126
	v_and_b32_e32 v131, 0xffff0000, v126
	v_lshlrev_b32_e32 v126, 16, v127
	v_and_b32_e32 v127, 0xffff0000, v127
	v_pk_fma_f32 v[122:123], v[122:123], s[60:61], v[124:125] op_sel_hi:[1,0,1]
	v_pk_fma_f32 v[120:121], v[120:121], s[60:61], v[128:129] op_sel_hi:[1,0,1]
	v_pk_fma_f32 v[124:125], v[118:119], s[60:61], v[126:127] op_sel_hi:[1,0,1]
	v_pk_fma_f32 v[126:127], v[116:117], s[60:61], v[130:131] op_sel_hi:[1,0,1]
	v_cvt_pk_bf16_f32 v116, v120, v121
	v_cvt_pk_bf16_f32 v117, v122, v123
	v_cvt_pk_bf16_f32 v118, v126, v127
	v_cvt_pk_bf16_f32 v119, v124, v125
	global_store_dwordx4 v[142:143], v[116:119], off offset:256
	s_nop 1
	v_mul_f32_e32 v116, v121, v121
	v_mul_f32_e32 v117, v123, v123
	v_fmac_f32_e32 v116, v120, v120
	v_fmac_f32_e32 v117, v122, v122
	v_add_f32_e32 v116, v116, v117
	v_mul_f32_e32 v117, v127, v127
	v_fmac_f32_e32 v117, v126, v126
	v_add_f32_e32 v116, v117, v116
	v_mul_f32_e32 v117, v125, v125
	v_fmac_f32_e32 v117, v124, v124
	v_add_f32_e32 v116, v117, v116
	v_add_f32_e32 v2, v2, v116
	ds_bpermute_b32 v116, v147, v2
	s_waitcnt lgkmcnt(0)
	v_add_f32_e32 v116, v2, v116
	ds_bpermute_b32 v117, v146, v116
	s_and_saveexec_b64 s[38:39], vcc
	s_cbranch_execz .LBB0_535
	v_lshl_add_u32 v2, v148, 4, s4
	v_lshl_add_u64 v[118:119], v[2:3], 2, s[58:59]
	s_waitcnt lgkmcnt(0)
	v_add_f32_e32 v2, v116, v117
	global_store_dword v[118:119], v2, off
; __device__ __forceinline__ float bf_lo(unsigned u) { return __uint_as_float(u << 16); }
; __device__ __forceinline__ float bf_hi(unsigned u) { return __uint_as_float(u & 0xffff0000u); }
; __device__ __forceinline__ u32x4 pack8(const f32x4 v0, const f32x4 v1) { u32x4 w; w.x = cvt_pk_bf16(v0[0], v0[1]); w.y = cvt_pk_bf16(v0[2], v0[3]); w.z = cvt_pk_bf16(v1[0], v1[1]); w.w = cvt_pk_bf16(v1[2], v1[3]); return w; }
;     __device__ __forceinline__ void operator()(const f32x4 (&acc)[2][2][4][2], const Unit& u, int wr, int wc, int fr, int fq) const {
;     ...
;                 for (int m = 0; m < 4; ++m) { const int r = row0 + ai * HALF + m * 16; float s = 0.f;
; #pragma unroll
;                     for (int bj = 0; bj < 2; ++bj) { const unsigned off = (unsigned)(r * 1024 + u.pn * BM + bj * HALF + wc * 32 + 8 * fq);
;                         const u32x4 bq = *(const u32x4*)(O + off);
;                         const f32x4 b0 = {bf_lo(bq.x), bf_hi(bq.x), bf_lo(bq.y), bf_hi(bq.y)}, b1 = {bf_lo(bq.z), bf_hi(bq.z), bf_lo(bq.w), bf_hi(bq.w)};
;                         const f32x4 h0 = b0 + acc[ai][bj][m][0] * alpha, h1 = b1 + acc[ai][bj][m][1] * alpha;
;                         *(u32x4*)(O + off) = pack8(h0, h1);
;                         s += (h0[0] * h0[0] + h0[1] * h0[1]) + (h0[2] * h0[2] + h0[3] * h0[3]) + (h1[0] * h1[0] + h1[1] * h1[1]) + (h1[2] * h1[2] + h1[3] * h1[3]); }
;                     s += __shfl_xor(s, 16); s += __shfl_xor(s, 32);
;                     if (fq == 0) ssq_out[(unsigned)(r * 16 + u.pn * 4 + wc)] = s;
;                     asm volatile("" ::: "memory"); }
.LBB0_535:
	s_or_b64 exec, exec, s[38:39]
	v_or_b32_e32 v118, 16, v148
	v_lshl_add_u32 v2, v118, 10, v149
	s_waitcnt lgkmcnt(0)
	v_lshl_add_u64 v[116:117], v[2:3], 1, s[62:63]
	s_waitcnt vmcnt(13)
	v_mov_b32_e32 v120, v166
	v_mov_b32_e32 v121, v167
	v_mov_b32_e32 v122, v168
	v_mov_b32_e32 v123, v169
	v_add_u32_e32 v231, 0x58000, v230
	global_load_dwordx4 v[166:169], v231, s[62:63] offset:0
	s_mov_b32 s61, s60
	s_mov_b32 s38, s60
	s_mov_b32 s39, s60
	s_waitcnt lgkmcnt(0)
	v_lshlrev_b32_e32 v124, 16, v120
	v_and_b32_e32 v125, 0xffff0000, v120
	v_lshlrev_b32_e32 v120, 16, v121
	v_and_b32_e32 v121, 0xffff0000, v121
	v_lshlrev_b32_e32 v126, 16, v122
	v_and_b32_e32 v127, 0xffff0000, v122
	v_lshlrev_b32_e32 v122, 16, v123
	v_and_b32_e32 v123, 0xffff0000, v123
	v_pk_fma_f32 v[114:115], v[114:115], s[38:39], v[120:121]
	v_pk_fma_f32 v[112:113], v[112:113], s[60:61], v[124:125]
	v_pk_fma_f32 v[120:121], v[110:111], s[38:39], v[122:123]
	v_pk_fma_f32 v[122:123], v[108:109], s[60:61], v[126:127]
	v_cvt_pk_bf16_f32 v108, v112, v113
	v_cvt_pk_bf16_f32 v109, v114, v115
	v_cvt_pk_bf16_f32 v110, v122, v123
	v_cvt_pk_bf16_f32 v111, v120, v121
	global_store_dwordx4 v[116:117], v[108:111], off
	v_mul_f32_e32 v2, v113, v113
	v_fmac_f32_e32 v2, v112, v112
	v_mul_f32_e32 v108, v115, v115
	v_fmac_f32_e32 v108, v114, v114
	v_add_f32_e32 v2, v2, v108
	v_mul_f32_e32 v108, v123, v123
	v_fmac_f32_e32 v108, v122, v122
	v_add_f32_e32 v2, v108, v2
	v_mul_f32_e32 v108, v121, v121
	v_fmac_f32_e32 v108, v120, v120
	v_add_f32_e32 v2, v108, v2
	s_waitcnt vmcnt(14)
	v_mov_b32_e32 v108, v170
	v_mov_b32_e32 v109, v171
	v_mov_b32_e32 v110, v172
	v_mov_b32_e32 v111, v173
	v_add_u32_e32 v231, 0x58000, v230
	global_load_dwordx4 v[170:173], v231, s[62:63] offset:256
	s_waitcnt lgkmcnt(0)
	v_lshlrev_b32_e32 v112, 16, v108
	v_and_b32_e32 v113, 0xffff0000, v108
	v_lshlrev_b32_e32 v108, 16, v109
	v_and_b32_e32 v109, 0xffff0000, v109
	v_lshlrev_b32_e32 v114, 16, v110
	v_and_b32_e32 v115, 0xffff0000, v110
	v_lshlrev_b32_e32 v110, 16, v111
	v_and_b32_e32 v111, 0xffff0000, v111
	v_pk_fma_f32 v[106:107], v[106:107], s[38:39], v[108:109]
	v_pk_fma_f32 v[104:105], v[104:105], s[60:61], v[112:113]
	v_pk_fma_f32 v[108:109], v[102:103], s[38:39], v[110:111]
	v_pk_fma_f32 v[110:111], v[100:101], s[60:61], v[114:115]
	v_cvt_pk_bf16_f32 v100, v104, v105
	v_cvt_pk_bf16_f32 v101, v106, v107
	v_cvt_pk_bf16_f32 v102, v110, v111
	v_cvt_pk_bf16_f32 v103, v108, v109
	global_store_dwordx4 v[116:117], v[100:103], off offset:256
	s_nop 1
	v_mul_f32_e32 v100, v105, v105
	v_mul_f32_e32 v101, v107, v107
	v_fmac_f32_e32 v100, v104, v104
	v_fmac_f32_e32 v101, v106, v106
	v_add_f32_e32 v100, v100, v101
	v_mul_f32_e32 v101, v111, v111
	v_fmac_f32_e32 v101, v110, v110
	v_add_f32_e32 v100, v101, v100
	v_mul_f32_e32 v101, v109, v109
	v_fmac_f32_e32 v101, v108, v108
	v_add_f32_e32 v100, v101, v100
	v_add_f32_e32 v2, v2, v100
	ds_bpermute_b32 v100, v147, v2
	s_waitcnt lgkmcnt(0)
	v_add_f32_e32 v100, v2, v100
	ds_bpermute_b32 v101, v146, v100
	s_and_saveexec_b64 s[50:51], vcc
	s_cbranch_execz .LBB0_537
	v_lshl_add_u32 v2, v118, 4, s4
	v_lshl_add_u64 v[102:103], v[2:3], 2, s[58:59]
	s_waitcnt lgkmcnt(0)
	v_add_f32_e32 v2, v100, v101
	global_store_dword v[102:103], v2, off
.LBB0_537:
	s_or_b64 exec, exec, s[50:51]
	v_or_b32_e32 v100, 32, v148
	v_lshl_add_u32 v2, v100, 10, v149
	v_lshl_add_u64 v[106:107], v[2:3], 1, s[62:63]
	s_waitcnt vmcnt(15)
	v_mov_b32_e32 v102, v174
	v_mov_b32_e32 v103, v175
	v_mov_b32_e32 v104, v176
	v_mov_b32_e32 v105, v177
	s_waitcnt lgkmcnt(0)
	v_lshlrev_b32_e32 v108, 16, v102
	v_and_b32_e32 v109, 0xffff0000, v102
	v_lshlrev_b32_e32 v102, 16, v103
	v_and_b32_e32 v103, 0xffff0000, v103
	v_lshlrev_b32_e32 v110, 16, v104
	v_and_b32_e32 v111, 0xffff0000, v104
	v_lshlrev_b32_e32 v104, 16, v105
	v_and_b32_e32 v105, 0xffff0000, v105
	v_pk_fma_f32 v[98:99], v[98:99], s[38:39], v[102:103]
	v_pk_fma_f32 v[96:97], v[96:97], s[60:61], v[108:109]
	v_pk_fma_f32 v[102:103], v[94:95], s[38:39], v[104:105]
	v_pk_fma_f32 v[104:105], v[92:93], s[60:61], v[110:111]
	v_cvt_pk_bf16_f32 v92, v96, v97
	v_cvt_pk_bf16_f32 v93, v98, v99
	v_cvt_pk_bf16_f32 v94, v104, v105
	v_cvt_pk_bf16_f32 v95, v102, v103
	global_store_dwordx4 v[106:107], v[92:95], off
	v_mul_f32_e32 v2, v97, v97
	v_fmac_f32_e32 v2, v96, v96
	v_mul_f32_e32 v92, v99, v99
	v_fmac_f32_e32 v92, v98, v98
	v_add_f32_e32 v2, v2, v92
	v_mul_f32_e32 v92, v105, v105
	v_fmac_f32_e32 v92, v104, v104
	v_add_f32_e32 v2, v92, v2
	v_mul_f32_e32 v92, v103, v103
	v_fmac_f32_e32 v92, v102, v102
	v_add_f32_e32 v2, v92, v2
	s_waitcnt vmcnt(15)
	v_mov_b32_e32 v92, v178
	v_mov_b32_e32 v93, v179
	v_mov_b32_e32 v94, v180
	v_mov_b32_e32 v95, v181
	s_waitcnt lgkmcnt(0)
	v_lshlrev_b32_e32 v96, 16, v92
	v_and_b32_e32 v97, 0xffff0000, v92
	v_lshlrev_b32_e32 v92, 16, v93
	v_and_b32_e32 v93, 0xffff0000, v93
	v_lshlrev_b32_e32 v98, 16, v94
	v_and_b32_e32 v99, 0xffff0000, v94
	v_lshlrev_b32_e32 v94, 16, v95
	v_and_b32_e32 v95, 0xffff0000, v95
	v_pk_fma_f32 v[90:91], v[90:91], s[38:39], v[92:93]
	v_pk_fma_f32 v[88:89], v[88:89], s[60:61], v[96:97]
	v_pk_fma_f32 v[92:93], v[86:87], s[38:39], v[94:95]
	v_pk_fma_f32 v[94:95], v[84:85], s[60:61], v[98:99]
	v_cvt_pk_bf16_f32 v84, v88, v89
	v_cvt_pk_bf16_f32 v85, v90, v91
	v_cvt_pk_bf16_f32 v86, v94, v95
	v_cvt_pk_bf16_f32 v87, v92, v93
	global_store_dwordx4 v[106:107], v[84:87], off offset:256
	s_nop 1
	v_mul_f32_e32 v84, v89, v89
	v_mul_f32_e32 v85, v91, v91
	v_fmac_f32_e32 v84, v88, v88
	v_fmac_f32_e32 v85, v90, v90
	v_add_f32_e32 v84, v84, v85
	v_mul_f32_e32 v85, v95, v95
	v_fmac_f32_e32 v85, v94, v94
	v_add_f32_e32 v84, v85, v84
	v_mul_f32_e32 v85, v93, v93
	v_fmac_f32_e32 v85, v92, v92
	v_add_f32_e32 v84, v85, v84
	v_add_f32_e32 v2, v2, v84
	ds_bpermute_b32 v84, v147, v2
	s_waitcnt lgkmcnt(0)
	v_add_f32_e32 v84, v2, v84
	ds_bpermute_b32 v85, v146, v84
	s_and_saveexec_b64 s[38:39], vcc
	s_cbranch_execz .LBB0_539
	v_lshl_add_u32 v2, v100, 4, s4
	v_lshl_add_u64 v[86:87], v[2:3], 2, s[58:59]
	s_waitcnt lgkmcnt(0)
	v_add_f32_e32 v2, v84, v85
	global_store_dword v[86:87], v2, off
; __device__ __forceinline__ float bf_lo(unsigned u) { return __uint_as_float(u << 16); }
; __device__ __forceinline__ float bf_hi(unsigned u) { return __uint_as_float(u & 0xffff0000u); }
; __device__ __forceinline__ u32x4 pack8(const f32x4 v0, const f32x4 v1) { u32x4 w; w.x = cvt_pk_bf16(v0[0], v0[1]); w.y = cvt_pk_bf16(v0[2], v0[3]); w.z = cvt_pk_bf16(v1[0], v1[1]); w.w = cvt_pk_bf16(v1[2], v1[3]); return w; }
;     __device__ __forceinline__ void operator()(const f32x4 (&acc)[2][2][4][2], const Unit& u, int wr, int wc, int fr, int fq) const {
;     ...
;                 for (int m = 0; m < 4; ++m) { const int r = row0 + ai * HALF + m * 16; float s = 0.f;
; #pragma unroll
;                     for (int bj = 0; bj < 2; ++bj) { const unsigned off = (unsigned)(r * 1024 + u.pn * BM + bj * HALF + wc * 32 + 8 * fq);
;                         const u32x4 bq = *(const u32x4*)(O + off);
;                         const f32x4 b0 = {bf_lo(bq.x), bf_hi(bq.x), bf_lo(bq.y), bf_hi(bq.y)}, b1 = {bf_lo(bq.z), bf_hi(bq.z), bf_lo(bq.w), bf_hi(bq.w)};
;                         const f32x4 h0 = b0 + acc[ai][bj][m][0] * alpha, h1 = b1 + acc[ai][bj][m][1] * alpha;
;                         *(u32x4*)(O + off) = pack8(h0, h1);
;                         s += (h0[0] * h0[0] + h0[1] * h0[1]) + (h0[2] * h0[2] + h0[3] * h0[3]) + (h1[0] * h1[0] + h1[1] * h1[1]) + (h1[2] * h1[2] + h1[3] * h1[3]); }
;                     s += __shfl_xor(s, 16); s += __shfl_xor(s, 32);
;                     if (fq == 0) ssq_out[(unsigned)(r * 16 + u.pn * 4 + wc)] = s;
;                     asm volatile("" ::: "memory"); }
.LBB0_539:
	s_or_b64 exec, exec, s[38:39]
	v_or_b32_e32 v86, 48, v148
	v_lshl_add_u32 v2, v86, 10, v149
	s_waitcnt lgkmcnt(0)
	v_lshl_add_u64 v[84:85], v[2:3], 1, s[62:63]
	s_waitcnt vmcnt(15)
	v_mov_b32_e32 v88, v194
	v_mov_b32_e32 v89, v195
	v_mov_b32_e32 v90, v196
	v_mov_b32_e32 v91, v197
	s_mov_b32 s38, s60
	s_mov_b32 s39, s60
	s_waitcnt lgkmcnt(0)
	v_lshlrev_b32_e32 v92, 16, v88
	v_and_b32_e32 v93, 0xffff0000, v88
	v_lshlrev_b32_e32 v88, 16, v89
	v_and_b32_e32 v89, 0xffff0000, v89
	v_lshlrev_b32_e32 v94, 16, v90
	v_and_b32_e32 v95, 0xffff0000, v90
	v_lshlrev_b32_e32 v90, 16, v91
	v_and_b32_e32 v91, 0xffff0000, v91
	v_pk_fma_f32 v[82:83], v[82:83], s[38:39], v[88:89]
	v_pk_fma_f32 v[80:81], v[80:81], s[60:61], v[92:93]
	v_pk_fma_f32 v[88:89], v[78:79], s[38:39], v[90:91]
	v_pk_fma_f32 v[90:91], v[76:77], s[60:61], v[94:95]
	v_cvt_pk_bf16_f32 v76, v80, v81
	v_cvt_pk_bf16_f32 v77, v82, v83
	v_cvt_pk_bf16_f32 v78, v90, v91
	v_cvt_pk_bf16_f32 v79, v88, v89
	global_store_dwordx4 v[84:85], v[76:79], off
	v_mul_f32_e32 v2, v81, v81
	v_fmac_f32_e32 v2, v80, v80
	v_mul_f32_e32 v76, v83, v83
	v_fmac_f32_e32 v76, v82, v82
	v_add_f32_e32 v2, v2, v76
	v_mul_f32_e32 v76, v91, v91
	v_fmac_f32_e32 v76, v90, v90
	v_add_f32_e32 v2, v76, v2
	v_mul_f32_e32 v76, v89, v89
	v_fmac_f32_e32 v76, v88, v88
	v_add_f32_e32 v2, v76, v2
	s_waitcnt vmcnt(15)
	v_mov_b32_e32 v76, v198
	v_mov_b32_e32 v77, v199
	v_mov_b32_e32 v78, v200
	v_mov_b32_e32 v79, v201
	s_waitcnt lgkmcnt(0)
	v_lshlrev_b32_e32 v80, 16, v76
	v_and_b32_e32 v81, 0xffff0000, v76
	v_lshlrev_b32_e32 v76, 16, v77
	v_and_b32_e32 v77, 0xffff0000, v77
	v_lshlrev_b32_e32 v82, 16, v78
	v_and_b32_e32 v83, 0xffff0000, v78
	v_lshlrev_b32_e32 v78, 16, v79
	v_and_b32_e32 v79, 0xffff0000, v79
	v_pk_fma_f32 v[74:75], v[74:75], s[38:39], v[76:77]
	v_pk_fma_f32 v[72:73], v[72:73], s[60:61], v[80:81]
	v_pk_fma_f32 v[76:77], v[70:71], s[38:39], v[78:79]
	v_pk_fma_f32 v[78:79], v[68:69], s[60:61], v[82:83]
	v_cvt_pk_bf16_f32 v68, v72, v73
	v_cvt_pk_bf16_f32 v69, v74, v75
	v_cvt_pk_bf16_f32 v70, v78, v79
	v_cvt_pk_bf16_f32 v71, v76, v77
	global_store_dwordx4 v[84:85], v[68:71], off offset:256
	s_nop 1
	v_mul_f32_e32 v68, v73, v73
	v_mul_f32_e32 v69, v75, v75
	v_fmac_f32_e32 v68, v72, v72
	v_fmac_f32_e32 v69, v74, v74
	v_add_f32_e32 v68, v68, v69
	v_mul_f32_e32 v69, v79, v79
	v_fmac_f32_e32 v69, v78, v78
	v_add_f32_e32 v68, v69, v68
	v_mul_f32_e32 v69, v77, v77
	v_fmac_f32_e32 v69, v76, v76
	v_add_f32_e32 v68, v69, v68
	v_add_f32_e32 v2, v2, v68
	ds_bpermute_b32 v68, v147, v2
	s_waitcnt lgkmcnt(0)
	v_add_f32_e32 v68, v2, v68
	ds_bpermute_b32 v69, v146, v68
	s_and_saveexec_b64 s[50:51], vcc
	s_cbranch_execz .LBB0_541
	v_lshl_add_u32 v2, v86, 4, s4
	v_lshl_add_u64 v[70:71], v[2:3], 2, s[58:59]
	s_waitcnt lgkmcnt(0)
	v_add_f32_e32 v2, v68, v69
	global_store_dword v[70:71], v2, off
.LBB0_541:
	s_or_b64 exec, exec, s[50:51]
	v_add_u32_e32 v68, 0x80, v148
	v_lshl_add_u32 v2, v68, 10, v149
	v_lshl_add_u64 v[74:75], v[2:3], 1, s[62:63]
	s_waitcnt vmcnt(15)
	v_mov_b32_e32 v70, v202
	v_mov_b32_e32 v71, v203
	v_mov_b32_e32 v72, v204
	v_mov_b32_e32 v73, v205
	s_waitcnt lgkmcnt(0)
	v_lshlrev_b32_e32 v76, 16, v70
	v_and_b32_e32 v77, 0xffff0000, v70
	v_lshlrev_b32_e32 v70, 16, v71
	v_and_b32_e32 v71, 0xffff0000, v71
	v_lshlrev_b32_e32 v78, 16, v72
	v_and_b32_e32 v79, 0xffff0000, v72
	v_lshlrev_b32_e32 v72, 16, v73
	v_and_b32_e32 v73, 0xffff0000, v73
	v_pk_fma_f32 v[66:67], v[66:67], s[38:39], v[70:71]
	v_pk_fma_f32 v[64:65], v[64:65], s[60:61], v[76:77]
	v_pk_fma_f32 v[70:71], v[62:63], s[38:39], v[72:73]
	v_pk_fma_f32 v[72:73], v[60:61], s[60:61], v[78:79]
	v_cvt_pk_bf16_f32 v60, v64, v65
	v_cvt_pk_bf16_f32 v61, v66, v67
	v_cvt_pk_bf16_f32 v62, v72, v73
	v_cvt_pk_bf16_f32 v63, v70, v71
	global_store_dwordx4 v[74:75], v[60:63], off
	v_mul_f32_e32 v2, v65, v65
	v_fmac_f32_e32 v2, v64, v64
	v_mul_f32_e32 v60, v67, v67
	v_fmac_f32_e32 v60, v66, v66
	v_add_f32_e32 v2, v2, v60
	v_mul_f32_e32 v60, v73, v73
	v_fmac_f32_e32 v60, v72, v72
	v_add_f32_e32 v2, v60, v2
	v_mul_f32_e32 v60, v71, v71
	v_fmac_f32_e32 v60, v70, v70
	v_add_f32_e32 v2, v60, v2
	s_waitcnt vmcnt(15)
	v_mov_b32_e32 v60, v206
	v_mov_b32_e32 v61, v207
	v_mov_b32_e32 v62, v208
	v_mov_b32_e32 v63, v209
	s_waitcnt lgkmcnt(0)
	v_lshlrev_b32_e32 v64, 16, v60
	v_and_b32_e32 v65, 0xffff0000, v60
	v_lshlrev_b32_e32 v60, 16, v61
	v_and_b32_e32 v61, 0xffff0000, v61
	v_lshlrev_b32_e32 v66, 16, v62
	v_and_b32_e32 v67, 0xffff0000, v62
	v_lshlrev_b32_e32 v62, 16, v63
	v_and_b32_e32 v63, 0xffff0000, v63
	v_pk_fma_f32 v[58:59], v[58:59], s[38:39], v[60:61]
	v_pk_fma_f32 v[56:57], v[56:57], s[60:61], v[64:65]
	v_pk_fma_f32 v[60:61], v[54:55], s[38:39], v[62:63]
	v_pk_fma_f32 v[62:63], v[52:53], s[60:61], v[66:67]
	v_cvt_pk_bf16_f32 v52, v56, v57
	v_cvt_pk_bf16_f32 v53, v58, v59
	v_cvt_pk_bf16_f32 v54, v62, v63
	v_cvt_pk_bf16_f32 v55, v60, v61
	global_store_dwordx4 v[74:75], v[52:55], off offset:256
	s_nop 1
	v_mul_f32_e32 v52, v57, v57
	v_mul_f32_e32 v53, v59, v59
	v_fmac_f32_e32 v52, v56, v56
	v_fmac_f32_e32 v53, v58, v58
	v_add_f32_e32 v52, v52, v53
	v_mul_f32_e32 v53, v63, v63
	v_fmac_f32_e32 v53, v62, v62
	v_add_f32_e32 v52, v53, v52
	v_mul_f32_e32 v53, v61, v61
	v_fmac_f32_e32 v53, v60, v60
	v_add_f32_e32 v52, v53, v52
	v_add_f32_e32 v2, v2, v52
	ds_bpermute_b32 v52, v147, v2
	s_waitcnt lgkmcnt(0)
	v_add_f32_e32 v52, v2, v52
	ds_bpermute_b32 v53, v146, v52
	s_and_saveexec_b64 s[38:39], vcc
	s_cbranch_execz .LBB0_543
	v_lshl_add_u32 v2, v68, 4, s4
	v_lshl_add_u64 v[54:55], v[2:3], 2, s[58:59]
	s_waitcnt lgkmcnt(0)
	v_add_f32_e32 v2, v52, v53
	global_store_dword v[54:55], v2, off
; __device__ __forceinline__ float bf_lo(unsigned u) { return __uint_as_float(u << 16); }
; __device__ __forceinline__ float bf_hi(unsigned u) { return __uint_as_float(u & 0xffff0000u); }
; __device__ __forceinline__ u32x4 pack8(const f32x4 v0, const f32x4 v1) { u32x4 w; w.x = cvt_pk_bf16(v0[0], v0[1]); w.y = cvt_pk_bf16(v0[2], v0[3]); w.z = cvt_pk_bf16(v1[0], v1[1]); w.w = cvt_pk_bf16(v1[2], v1[3]); return w; }
;     __device__ __forceinline__ void operator()(const f32x4 (&acc)[2][2][4][2], const Unit& u, int wr, int wc, int fr, int fq) const {
;     ...
;                 for (int m = 0; m < 4; ++m) { const int r = row0 + ai * HALF + m * 16; float s = 0.f;
; #pragma unroll
;                     for (int bj = 0; bj < 2; ++bj) { const unsigned off = (unsigned)(r * 1024 + u.pn * BM + bj * HALF + wc * 32 + 8 * fq);
;                         const u32x4 bq = *(const u32x4*)(O + off);
;                         const f32x4 b0 = {bf_lo(bq.x), bf_hi(bq.x), bf_lo(bq.y), bf_hi(bq.y)}, b1 = {bf_lo(bq.z), bf_hi(bq.z), bf_lo(bq.w), bf_hi(bq.w)};
;                         const f32x4 h0 = b0 + acc[ai][bj][m][0] * alpha, h1 = b1 + acc[ai][bj][m][1] * alpha;
;                         *(u32x4*)(O + off) = pack8(h0, h1);
;                         s += (h0[0] * h0[0] + h0[1] * h0[1]) + (h0[2] * h0[2] + h0[3] * h0[3]) + (h1[0] * h1[0] + h1[1] * h1[1]) + (h1[2] * h1[2] + h1[3] * h1[3]); }
;                     s += __shfl_xor(s, 16); s += __shfl_xor(s, 32);
;                     if (fq == 0) ssq_out[(unsigned)(r * 16 + u.pn * 4 + wc)] = s;
;                     asm volatile("" ::: "memory"); }
.LBB0_543:
	s_or_b64 exec, exec, s[38:39]
	v_add_u32_e32 v54, 0x90, v148
	v_lshl_add_u32 v2, v54, 10, v149
	s_waitcnt lgkmcnt(0)
	v_lshl_add_u64 v[52:53], v[2:3], 1, s[62:63]
	s_waitcnt vmcnt(15)
	v_mov_b32_e32 v56, v220
	v_mov_b32_e32 v57, v221
	v_mov_b32_e32 v58, v222
	v_mov_b32_e32 v59, v223
	s_mov_b32 s38, s60
	s_mov_b32 s39, s60
	s_waitcnt lgkmcnt(0)
	v_lshlrev_b32_e32 v60, 16, v56
	v_and_b32_e32 v61, 0xffff0000, v56
	v_lshlrev_b32_e32 v56, 16, v57
	v_and_b32_e32 v57, 0xffff0000, v57
	v_lshlrev_b32_e32 v62, 16, v58
	v_and_b32_e32 v63, 0xffff0000, v58
	v_lshlrev_b32_e32 v58, 16, v59
	v_and_b32_e32 v59, 0xffff0000, v59
	v_pk_fma_f32 v[50:51], v[50:51], s[38:39], v[56:57]
	v_pk_fma_f32 v[48:49], v[48:49], s[60:61], v[60:61]
	v_pk_fma_f32 v[56:57], v[46:47], s[38:39], v[58:59]
	v_pk_fma_f32 v[58:59], v[44:45], s[60:61], v[62:63]
	v_cvt_pk_bf16_f32 v44, v48, v49
	v_cvt_pk_bf16_f32 v45, v50, v51
	v_cvt_pk_bf16_f32 v46, v58, v59
	v_cvt_pk_bf16_f32 v47, v56, v57
	global_store_dwordx4 v[52:53], v[44:47], off
	v_mul_f32_e32 v2, v49, v49
	v_fmac_f32_e32 v2, v48, v48
	v_mul_f32_e32 v44, v51, v51
	v_fmac_f32_e32 v44, v50, v50
	v_add_f32_e32 v2, v2, v44
	v_mul_f32_e32 v44, v59, v59
	v_fmac_f32_e32 v44, v58, v58
	v_add_f32_e32 v2, v44, v2
	v_mul_f32_e32 v44, v57, v57
	v_fmac_f32_e32 v44, v56, v56
	v_add_f32_e32 v2, v44, v2
	s_waitcnt vmcnt(15)
	v_mov_b32_e32 v44, v224
	v_mov_b32_e32 v45, v225
	v_mov_b32_e32 v46, v226
	v_mov_b32_e32 v47, v227
	s_waitcnt lgkmcnt(0)
	v_lshlrev_b32_e32 v48, 16, v44
	v_and_b32_e32 v49, 0xffff0000, v44
	v_lshlrev_b32_e32 v44, 16, v45
	v_and_b32_e32 v45, 0xffff0000, v45
	v_lshlrev_b32_e32 v50, 16, v46
	v_and_b32_e32 v51, 0xffff0000, v46
	v_lshlrev_b32_e32 v46, 16, v47
	v_and_b32_e32 v47, 0xffff0000, v47
	v_pk_fma_f32 v[42:43], v[42:43], s[38:39], v[44:45]
	v_pk_fma_f32 v[40:41], v[40:41], s[60:61], v[48:49]
	v_pk_fma_f32 v[44:45], v[38:39], s[38:39], v[46:47]
	v_pk_fma_f32 v[46:47], v[36:37], s[60:61], v[50:51]
	v_cvt_pk_bf16_f32 v36, v40, v41
	v_cvt_pk_bf16_f32 v37, v42, v43
	v_cvt_pk_bf16_f32 v38, v46, v47
	v_cvt_pk_bf16_f32 v39, v44, v45
	global_store_dwordx4 v[52:53], v[36:39], off offset:256
	s_nop 1
	v_mul_f32_e32 v36, v41, v41
	v_mul_f32_e32 v37, v43, v43
	v_fmac_f32_e32 v36, v40, v40
	v_fmac_f32_e32 v37, v42, v42
	v_add_f32_e32 v36, v36, v37
	v_mul_f32_e32 v37, v47, v47
	v_fmac_f32_e32 v37, v46, v46
	v_add_f32_e32 v36, v37, v36
	v_mul_f32_e32 v37, v45, v45
	v_fmac_f32_e32 v37, v44, v44
	v_add_f32_e32 v36, v37, v36
	v_add_f32_e32 v2, v2, v36
	ds_bpermute_b32 v36, v147, v2
	s_waitcnt lgkmcnt(0)
	v_add_f32_e32 v36, v2, v36
	ds_bpermute_b32 v37, v146, v36
	s_and_saveexec_b64 s[50:51], vcc
	s_cbranch_execz .LBB0_545
	v_lshl_add_u32 v2, v54, 4, s4
	v_lshl_add_u64 v[38:39], v[2:3], 2, s[58:59]
	s_waitcnt lgkmcnt(0)
	v_add_f32_e32 v2, v36, v37
	global_store_dword v[38:39], v2, off
; __device__ __forceinline__ float bf_lo(unsigned u) { return __uint_as_float(u << 16); }
; __device__ __forceinline__ float bf_hi(unsigned u) { return __uint_as_float(u & 0xffff0000u); }
; __device__ __forceinline__ u32x4 pack8(const f32x4 v0, const f32x4 v1) { u32x4 w; w.x = cvt_pk_bf16(v0[0], v0[1]); w.y = cvt_pk_bf16(v0[2], v0[3]); w.z = cvt_pk_bf16(v1[0], v1[1]); w.w = cvt_pk_bf16(v1[2], v1[3]); return w; }
;     __device__ __forceinline__ void operator()(const f32x4 (&acc)[2][2][4][2], const Unit& u, int wr, int wc, int fr, int fq) const {
;     ...
;                 for (int m = 0; m < 4; ++m) { const int r = row0 + ai * HALF + m * 16; float s = 0.f;
; #pragma unroll
;                     for (int bj = 0; bj < 2; ++bj) { const unsigned off = (unsigned)(r * 1024 + u.pn * BM + bj * HALF + wc * 32 + 8 * fq);
;                         const u32x4 bq = *(const u32x4*)(O + off);
;                         const f32x4 b0 = {bf_lo(bq.x), bf_hi(bq.x), bf_lo(bq.y), bf_hi(bq.y)}, b1 = {bf_lo(bq.z), bf_hi(bq.z), bf_lo(bq.w), bf_hi(bq.w)};
;                         const f32x4 h0 = b0 + acc[ai][bj][m][0] * alpha, h1 = b1 + acc[ai][bj][m][1] * alpha;
;                         *(u32x4*)(O + off) = pack8(h0, h1);
;                         s += (h0[0] * h0[0] + h0[1] * h0[1]) + (h0[2] * h0[2] + h0[3] * h0[3]) + (h1[0] * h1[0] + h1[1] * h1[1]) + (h1[2] * h1[2] + h1[3] * h1[3]); }
;                     s += __shfl_xor(s, 16); s += __shfl_xor(s, 32);
;                     if (fq == 0) ssq_out[(unsigned)(r * 16 + u.pn * 4 + wc)] = s;
;                     asm volatile("" ::: "memory"); }
.LBB0_545:
	s_or_b64 exec, exec, s[50:51]
	v_add_u32_e32 v36, 0xa0, v148
	v_lshl_add_u32 v2, v36, 10, v149
	v_lshl_add_u64 v[42:43], v[2:3], 1, s[62:63]
	s_waitcnt vmcnt(15)
	v_mov_b32_e32 v38, v158
	v_mov_b32_e32 v39, v159
	v_mov_b32_e32 v40, v160
	v_mov_b32_e32 v41, v161
	s_waitcnt lgkmcnt(0)
	v_lshlrev_b32_e32 v44, 16, v38
	v_and_b32_e32 v45, 0xffff0000, v38
	v_lshlrev_b32_e32 v38, 16, v39
	v_and_b32_e32 v39, 0xffff0000, v39
	v_lshlrev_b32_e32 v46, 16, v40
	v_and_b32_e32 v47, 0xffff0000, v40
	v_lshlrev_b32_e32 v40, 16, v41
	v_and_b32_e32 v41, 0xffff0000, v41
	v_pk_fma_f32 v[34:35], v[34:35], s[38:39], v[38:39]
	v_pk_fma_f32 v[32:33], v[32:33], s[60:61], v[44:45]
	v_pk_fma_f32 v[38:39], v[30:31], s[38:39], v[40:41]
	v_pk_fma_f32 v[40:41], v[28:29], s[60:61], v[46:47]
	v_cvt_pk_bf16_f32 v28, v32, v33
	v_cvt_pk_bf16_f32 v29, v34, v35
	v_cvt_pk_bf16_f32 v30, v40, v41
	v_cvt_pk_bf16_f32 v31, v38, v39
	global_store_dwordx4 v[42:43], v[28:31], off
	v_mul_f32_e32 v2, v33, v33
	v_fmac_f32_e32 v2, v32, v32
	v_mul_f32_e32 v28, v35, v35
	v_fmac_f32_e32 v28, v34, v34
	v_add_f32_e32 v2, v2, v28
	v_mul_f32_e32 v28, v41, v41
	v_fmac_f32_e32 v28, v40, v40
	v_add_f32_e32 v2, v28, v2
	v_mul_f32_e32 v28, v39, v39
	v_fmac_f32_e32 v28, v38, v38
	v_add_f32_e32 v2, v28, v2
	s_waitcnt vmcnt(14)
	v_mov_b32_e32 v28, v162
	v_mov_b32_e32 v29, v163
	v_mov_b32_e32 v30, v164
	v_mov_b32_e32 v31, v165
	s_waitcnt lgkmcnt(0)
	v_lshlrev_b32_e32 v32, 16, v28
	v_and_b32_e32 v33, 0xffff0000, v28
	v_lshlrev_b32_e32 v28, 16, v29
	v_and_b32_e32 v29, 0xffff0000, v29
	v_lshlrev_b32_e32 v34, 16, v30
	v_and_b32_e32 v35, 0xffff0000, v30
	v_lshlrev_b32_e32 v30, 16, v31
	v_and_b32_e32 v31, 0xffff0000, v31
	v_pk_fma_f32 v[26:27], v[26:27], s[38:39], v[28:29]
	v_pk_fma_f32 v[24:25], v[24:25], s[60:61], v[32:33]
	v_pk_fma_f32 v[28:29], v[22:23], s[38:39], v[30:31]
	v_pk_fma_f32 v[30:31], v[20:21], s[60:61], v[34:35]
	v_cvt_pk_bf16_f32 v20, v24, v25
	v_cvt_pk_bf16_f32 v21, v26, v27
	v_cvt_pk_bf16_f32 v22, v30, v31
	v_cvt_pk_bf16_f32 v23, v28, v29
	global_store_dwordx4 v[42:43], v[20:23], off offset:256
	s_nop 1
	v_mul_f32_e32 v20, v25, v25
	v_mul_f32_e32 v21, v27, v27
	v_fmac_f32_e32 v20, v24, v24
	v_fmac_f32_e32 v21, v26, v26
	v_add_f32_e32 v20, v20, v21
	v_mul_f32_e32 v21, v31, v31
	v_fmac_f32_e32 v21, v30, v30
	v_add_f32_e32 v20, v21, v20
	v_mul_f32_e32 v21, v29, v29
	v_fmac_f32_e32 v21, v28, v28
	v_add_f32_e32 v20, v21, v20
	v_add_f32_e32 v2, v2, v20
	ds_bpermute_b32 v20, v147, v2
	s_waitcnt lgkmcnt(0)
	v_add_f32_e32 v20, v2, v20
	ds_bpermute_b32 v21, v146, v20
	s_and_saveexec_b64 s[38:39], vcc
	s_cbranch_execz .LBB0_547
	v_lshl_add_u32 v2, v36, 4, s4
	v_lshl_add_u64 v[22:23], v[2:3], 2, s[58:59]
	s_waitcnt lgkmcnt(0)
	v_add_f32_e32 v2, v20, v21
	global_store_dword v[22:23], v2, off
.LBB0_547:
	s_or_b64 exec, exec, s[38:39]
	v_add_u32_e32 v22, 0xb0, v148
	v_lshl_add_u32 v2, v22, 10, v149
	s_waitcnt lgkmcnt(0)
	v_lshl_add_u64 v[20:21], v[2:3], 1, s[62:63]
	s_waitcnt vmcnt(13)
	v_mov_b32_e32 v24, v166
	v_mov_b32_e32 v25, v167
	v_mov_b32_e32 v26, v168
	v_mov_b32_e32 v27, v169
	s_mov_b32 s38, s60
	s_mov_b32 s39, s60
	s_waitcnt lgkmcnt(0)
	v_lshlrev_b32_e32 v28, 16, v24
	v_and_b32_e32 v29, 0xffff0000, v24
	v_lshlrev_b32_e32 v24, 16, v25
	v_and_b32_e32 v25, 0xffff0000, v25
	v_lshlrev_b32_e32 v30, 16, v26
	v_and_b32_e32 v31, 0xffff0000, v26
	v_lshlrev_b32_e32 v26, 16, v27
	v_and_b32_e32 v27, 0xffff0000, v27
	v_pk_fma_f32 v[18:19], v[18:19], s[38:39], v[24:25]
	v_pk_fma_f32 v[16:17], v[16:17], s[60:61], v[28:29]
	v_pk_fma_f32 v[24:25], v[14:15], s[38:39], v[26:27]
	v_pk_fma_f32 v[26:27], v[12:13], s[60:61], v[30:31]
	v_cvt_pk_bf16_f32 v12, v16, v17
	v_cvt_pk_bf16_f32 v13, v18, v19
	v_cvt_pk_bf16_f32 v14, v26, v27
	v_cvt_pk_bf16_f32 v15, v24, v25
	global_store_dwordx4 v[20:21], v[12:15], off
	v_mul_f32_e32 v2, v17, v17
	v_fmac_f32_e32 v2, v16, v16
	v_mul_f32_e32 v12, v19, v19
	v_fmac_f32_e32 v12, v18, v18
	v_add_f32_e32 v2, v2, v12
	v_mul_f32_e32 v12, v27, v27
	v_fmac_f32_e32 v12, v26, v26
	v_add_f32_e32 v2, v12, v2
	v_mul_f32_e32 v12, v25, v25
	v_fmac_f32_e32 v12, v24, v24
	v_add_f32_e32 v2, v12, v2
	s_waitcnt vmcnt(12)
	v_mov_b32_e32 v12, v170
	v_mov_b32_e32 v13, v171
	v_mov_b32_e32 v14, v172
	v_mov_b32_e32 v15, v173
	s_waitcnt lgkmcnt(0)
	v_lshlrev_b32_e32 v16, 16, v12
	v_and_b32_e32 v17, 0xffff0000, v12
	v_lshlrev_b32_e32 v12, 16, v13
	v_and_b32_e32 v13, 0xffff0000, v13
	v_lshlrev_b32_e32 v18, 16, v14
	v_and_b32_e32 v19, 0xffff0000, v14
	v_lshlrev_b32_e32 v14, 16, v15
	v_and_b32_e32 v15, 0xffff0000, v15
	v_pk_fma_f32 v[10:11], v[10:11], s[38:39], v[12:13]
	v_pk_fma_f32 v[8:9], v[8:9], s[60:61], v[16:17]
	v_pk_fma_f32 v[12:13], v[6:7], s[38:39], v[14:15]
	v_pk_fma_f32 v[14:15], v[4:5], s[60:61], v[18:19]
	v_cvt_pk_bf16_f32 v4, v8, v9
	v_cvt_pk_bf16_f32 v5, v10, v11
	v_cvt_pk_bf16_f32 v6, v14, v15
	v_cvt_pk_bf16_f32 v7, v12, v13
	global_store_dwordx4 v[20:21], v[4:7], off offset:256
	s_nop 1
	v_mul_f32_e32 v4, v9, v9
	v_mul_f32_e32 v5, v11, v11
	v_fmac_f32_e32 v4, v8, v8
	v_fmac_f32_e32 v5, v10, v10
	v_add_f32_e32 v4, v4, v5
	v_mul_f32_e32 v5, v15, v15
	v_fmac_f32_e32 v5, v14, v14
	v_add_f32_e32 v4, v5, v4
	v_mul_f32_e32 v5, v13, v13
	v_fmac_f32_e32 v5, v12, v12
	v_add_f32_e32 v4, v5, v4
	v_add_f32_e32 v2, v2, v4
	ds_bpermute_b32 v4, v147, v2
	s_waitcnt lgkmcnt(0)
	v_add_f32_e32 v4, v2, v4
	ds_bpermute_b32 v5, v146, v4
	s_and_saveexec_b64 s[38:39], vcc
	s_cbranch_execz .LBB0_549
	v_lshl_add_u32 v2, v22, 4, s4
	v_lshl_add_u64 v[6:7], v[2:3], 2, s[58:59]
	s_waitcnt lgkmcnt(0)
	v_add_f32_e32 v2, v4, v5
	global_store_dword v[6:7], v2, off
